# GEMM K-loops: s_setprio moved outside the barrier-to-barrier MFMA window (raise before the pre-MFMA barrier, drop after the post-MFMA barrier)
# baseline (speedup 1.0000x reference)
.LBB0_224:
	s_add_u32 s44, s38, 0x100
	s_addc_u32 s45, s39, 0
	s_add_i32 s30, 0, 0x10000
	s_cmp_eq_u32 s73, 12
	s_cselect_b32 s49, s9, s45
	s_cselect_b32 s48, s11, s44
	v_add_u32_e32 v138, s30, v141
	s_cselect_b32 s47, s20, s29
	s_cselect_b32 s46, s21, s27
	s_add_i32 s83, 0, 0x14000
	ds_read_b128 v[148:151], v138
	ds_read_b128 v[152:155], v138 offset:1024
	ds_read_b128 v[156:159], v138 offset:2048
	ds_read_b128 v[160:163], v138 offset:3072
	v_add_u32_e32 v138, s83, v141
	ds_read_b128 v[164:167], v138
	ds_read_b128 v[168:171], v138 offset:1024
	ds_read_b128 v[172:175], v138 offset:2048
	ds_read_b128 v[198:201], v138 offset:3072
	v_lshl_add_u64 v[138:139], s[38:39], 0, v[136:137]
	s_add_i32 m0, s40, 0xc000
	ds_read_b128 v[202:205], v145
	ds_read_b128 v[206:209], v145 offset:1024
	ds_read_b128 v[210:213], v145 offset:2048
	ds_read_b128 v[214:217], v145 offset:3072
	ds_read_b128 v[218:221], v145 offset:4096
	ds_read_b128 v[222:225], v145 offset:5120
	ds_read_b128 v[226:229], v145 offset:6144
	ds_read_b128 v[238:241], v145 offset:7168
	global_load_lds_dwordx4 v[138:139], off
	v_lshl_add_u64 v[138:139], s[38:39], 0, v[134:135]
	s_add_i32 m0, s40, 0xe000
	s_nop 0
	global_load_lds_dwordx4 v[138:139], off
	s_waitcnt vmcnt(8)
	s_waitcnt lgkmcnt(0)
	s_setprio 1
	s_barrier
	v_mfma_f32_16x16x32_bf16 v[124:127], v[148:151], v[202:205], v[124:127]
	v_mfma_f32_16x16x32_bf16 v[120:123], v[156:159], v[202:205], v[120:123]
	v_mfma_f32_16x16x32_bf16 v[116:119], v[148:151], v[210:213], v[116:119]
	v_mfma_f32_16x16x32_bf16 v[112:115], v[156:159], v[210:213], v[112:115]
	v_mfma_f32_16x16x32_bf16 v[108:111], v[148:151], v[218:221], v[108:111]
	v_mfma_f32_16x16x32_bf16 v[104:107], v[156:159], v[218:221], v[104:107]
	v_mfma_f32_16x16x32_bf16 v[100:103], v[148:151], v[226:229], v[100:103]
	v_mfma_f32_16x16x32_bf16 v[96:99], v[156:159], v[226:229], v[96:99]
	v_mfma_f32_16x16x32_bf16 v[124:127], v[152:155], v[206:209], v[124:127]
	v_mfma_f32_16x16x32_bf16 v[120:123], v[160:163], v[206:209], v[120:123]
	v_mfma_f32_16x16x32_bf16 v[116:119], v[152:155], v[214:217], v[116:119]
	v_mfma_f32_16x16x32_bf16 v[112:115], v[160:163], v[214:217], v[112:115]
	v_mfma_f32_16x16x32_bf16 v[108:111], v[152:155], v[222:225], v[108:111]
	v_mfma_f32_16x16x32_bf16 v[104:107], v[160:163], v[222:225], v[104:107]
	v_mfma_f32_16x16x32_bf16 v[100:103], v[152:155], v[238:241], v[100:103]
	v_mfma_f32_16x16x32_bf16 v[96:99], v[160:163], v[238:241], v[96:99]
	v_mfma_f32_16x16x32_bf16 v[60:63], v[164:167], v[202:205], v[60:63]
	v_mfma_f32_16x16x32_bf16 v[56:59], v[172:175], v[202:205], v[56:59]
	v_mfma_f32_16x16x32_bf16 v[52:55], v[164:167], v[210:213], v[52:55]
	v_mfma_f32_16x16x32_bf16 v[48:51], v[172:175], v[210:213], v[48:51]
	v_mfma_f32_16x16x32_bf16 v[44:47], v[164:167], v[218:221], v[44:47]
	v_mfma_f32_16x16x32_bf16 v[40:43], v[172:175], v[218:221], v[40:43]
	v_mfma_f32_16x16x32_bf16 v[36:39], v[164:167], v[226:229], v[36:39]
	v_mfma_f32_16x16x32_bf16 v[32:35], v[172:175], v[226:229], v[32:35]
	v_mfma_f32_16x16x32_bf16 v[60:63], v[168:171], v[206:209], v[60:63]
	v_mfma_f32_16x16x32_bf16 v[56:59], v[198:201], v[206:209], v[56:59]
	v_mfma_f32_16x16x32_bf16 v[52:55], v[168:171], v[214:217], v[52:55]
	v_mfma_f32_16x16x32_bf16 v[48:51], v[198:201], v[214:217], v[48:51]
	v_mfma_f32_16x16x32_bf16 v[44:47], v[168:171], v[222:225], v[44:47]
	v_mfma_f32_16x16x32_bf16 v[40:43], v[198:201], v[222:225], v[40:43]
	v_mfma_f32_16x16x32_bf16 v[36:39], v[168:171], v[238:241], v[36:39]
	v_mfma_f32_16x16x32_bf16 v[32:35], v[198:201], v[238:241], v[32:35]
	s_barrier
	s_setprio 0
	s_add_i32 s30, s30, s5
	v_lshl_add_u64 v[138:139], s[46:47], 0, v[130:131]
	s_mov_b32 m0, s30
	ds_read_b128 v[202:205], v145 offset:16384
	ds_read_b128 v[206:209], v145 offset:17408
	ds_read_b128 v[210:213], v145 offset:18432
	ds_read_b128 v[214:217], v145 offset:19456
	ds_read_b128 v[218:221], v145 offset:20480
	ds_read_b128 v[222:225], v145 offset:21504
	ds_read_b128 v[226:229], v145 offset:22528
	ds_read_b128 v[238:241], v145 offset:23552
	global_load_lds_dwordx4 v[138:139], off
	s_add_i32 m0, s30, 0x2000
	s_add_u32 s30, s46, 0x40000
	v_lshl_add_u64 v[176:177], s[46:47], 0, v[132:133]
	s_addc_u32 s31, s47, 0
	s_add_i32 s38, s83, s5
	global_load_lds_dwordx4 v[176:177], off
	v_lshl_add_u64 v[242:243], s[30:31], 0, v[130:131]
	s_mov_b32 m0, s38
	v_lshl_add_u64 v[244:245], s[48:49], 0, v[132:133]
	global_load_lds_dwordx4 v[242:243], off
	v_lshl_add_u64 v[242:243], s[30:31], 0, v[132:133]
	s_add_i32 m0, s38, 0x2000
	s_nop 0
	global_load_lds_dwordx4 v[242:243], off
	v_lshl_add_u64 v[242:243], s[48:49], 0, v[130:131]
	s_mov_b32 m0, s40
	s_nop 0
	global_load_lds_dwordx4 v[242:243], off
	s_mov_b32 m0, s41
	s_nop 0
	global_load_lds_dwordx4 v[244:245], off
	s_waitcnt vmcnt(8)
	s_waitcnt lgkmcnt(0)
	s_setprio 1
	s_barrier
	v_mfma_f32_16x16x32_bf16 v[92:95], v[148:151], v[202:205], v[92:95]
	v_mfma_f32_16x16x32_bf16 v[88:91], v[156:159], v[202:205], v[88:91]
	v_mfma_f32_16x16x32_bf16 v[84:87], v[148:151], v[210:213], v[84:87]
	v_mfma_f32_16x16x32_bf16 v[80:83], v[156:159], v[210:213], v[80:83]
	v_mfma_f32_16x16x32_bf16 v[76:79], v[148:151], v[218:221], v[76:79]
	v_mfma_f32_16x16x32_bf16 v[72:75], v[156:159], v[218:221], v[72:75]
	v_mfma_f32_16x16x32_bf16 v[68:71], v[148:151], v[226:229], v[68:71]
	v_mfma_f32_16x16x32_bf16 v[64:67], v[156:159], v[226:229], v[64:67]
	v_mfma_f32_16x16x32_bf16 v[92:95], v[152:155], v[206:209], v[92:95]
	v_mfma_f32_16x16x32_bf16 v[88:91], v[160:163], v[206:209], v[88:91]
	v_mfma_f32_16x16x32_bf16 v[84:87], v[152:155], v[214:217], v[84:87]
	v_mfma_f32_16x16x32_bf16 v[80:83], v[160:163], v[214:217], v[80:83]
	v_mfma_f32_16x16x32_bf16 v[76:79], v[152:155], v[222:225], v[76:79]
	v_mfma_f32_16x16x32_bf16 v[72:75], v[160:163], v[222:225], v[72:75]
	v_mfma_f32_16x16x32_bf16 v[68:71], v[152:155], v[238:241], v[68:71]
	v_mfma_f32_16x16x32_bf16 v[64:67], v[160:163], v[238:241], v[64:67]
	v_mfma_f32_16x16x32_bf16 v[28:31], v[164:167], v[202:205], v[28:31]
	v_mfma_f32_16x16x32_bf16 v[24:27], v[172:175], v[202:205], v[24:27]
	v_mfma_f32_16x16x32_bf16 v[20:23], v[164:167], v[210:213], v[20:23]
	v_mfma_f32_16x16x32_bf16 v[16:19], v[172:175], v[210:213], v[16:19]
	v_mfma_f32_16x16x32_bf16 v[12:15], v[164:167], v[218:221], v[12:15]
	v_mfma_f32_16x16x32_bf16 v[8:11], v[172:175], v[218:221], v[8:11]
	v_mfma_f32_16x16x32_bf16 v[4:7], v[164:167], v[226:229], v[4:7]
	v_mfma_f32_16x16x32_bf16 v[0:3], v[172:175], v[226:229], v[0:3]
	v_mfma_f32_16x16x32_bf16 v[28:31], v[168:171], v[206:209], v[28:31]
	v_mfma_f32_16x16x32_bf16 v[24:27], v[198:201], v[206:209], v[24:27]
	v_mfma_f32_16x16x32_bf16 v[20:23], v[168:171], v[214:217], v[20:23]
	v_mfma_f32_16x16x32_bf16 v[16:19], v[198:201], v[214:217], v[16:19]
	v_mfma_f32_16x16x32_bf16 v[12:15], v[168:171], v[222:225], v[12:15]
	v_mfma_f32_16x16x32_bf16 v[8:11], v[198:201], v[222:225], v[8:11]
	v_mfma_f32_16x16x32_bf16 v[4:7], v[168:171], v[238:241], v[4:7]
	v_mfma_f32_16x16x32_bf16 v[0:3], v[198:201], v[238:241], v[0:3]
	s_barrier
	s_setprio 0
	s_add_i32 s38, 0, 0x18000
	v_add_u32_e32 v147, s38, v141
	s_add_i32 s39, 0, 0x1c000
	ds_read_b128 v[148:151], v147
	ds_read_b128 v[152:155], v147 offset:1024
	ds_read_b128 v[156:159], v147 offset:2048
	ds_read_b128 v[160:163], v147 offset:3072
	v_add_u32_e32 v147, s39, v141
	ds_read_b128 v[164:167], v147
	ds_read_b128 v[168:171], v147 offset:1024
	ds_read_b128 v[172:175], v147 offset:2048
	ds_read_b128 v[198:201], v147 offset:3072
	s_add_u32 s30, s48, 0x40000
	s_addc_u32 s31, s49, 0
	s_mov_b32 m0, s42
	v_lshl_add_u64 v[246:247], s[30:31], 0, v[130:131]
	ds_read_b128 v[202:205], v145 offset:32768
	ds_read_b128 v[206:209], v145 offset:33792
	ds_read_b128 v[210:213], v145 offset:34816
	ds_read_b128 v[214:217], v145 offset:35840
	ds_read_b128 v[218:221], v145 offset:36864
	ds_read_b128 v[222:225], v145 offset:37888
	ds_read_b128 v[226:229], v145 offset:38912
	ds_read_b128 v[238:241], v145 offset:39936
	global_load_lds_dwordx4 v[246:247], off
	v_lshl_add_u64 v[246:247], s[30:31], 0, v[132:133]
	s_mov_b32 m0, s43
	s_nop 0
	global_load_lds_dwordx4 v[246:247], off
	s_waitcnt vmcnt(8)
	s_waitcnt lgkmcnt(0)
	s_setprio 1
	s_barrier
	v_mfma_f32_16x16x32_bf16 v[124:127], v[148:151], v[202:205], v[124:127]
	v_mfma_f32_16x16x32_bf16 v[120:123], v[156:159], v[202:205], v[120:123]
	v_mfma_f32_16x16x32_bf16 v[116:119], v[148:151], v[210:213], v[116:119]
	v_mfma_f32_16x16x32_bf16 v[112:115], v[156:159], v[210:213], v[112:115]
	v_mfma_f32_16x16x32_bf16 v[108:111], v[148:151], v[218:221], v[108:111]
	v_mfma_f32_16x16x32_bf16 v[104:107], v[156:159], v[218:221], v[104:107]
	v_mfma_f32_16x16x32_bf16 v[100:103], v[148:151], v[226:229], v[100:103]
	v_mfma_f32_16x16x32_bf16 v[96:99], v[156:159], v[226:229], v[96:99]
	v_mfma_f32_16x16x32_bf16 v[124:127], v[152:155], v[206:209], v[124:127]
	v_mfma_f32_16x16x32_bf16 v[120:123], v[160:163], v[206:209], v[120:123]
	v_mfma_f32_16x16x32_bf16 v[116:119], v[152:155], v[214:217], v[116:119]
	v_mfma_f32_16x16x32_bf16 v[112:115], v[160:163], v[214:217], v[112:115]
	v_mfma_f32_16x16x32_bf16 v[108:111], v[152:155], v[222:225], v[108:111]
	v_mfma_f32_16x16x32_bf16 v[104:107], v[160:163], v[222:225], v[104:107]
	v_mfma_f32_16x16x32_bf16 v[100:103], v[152:155], v[238:241], v[100:103]
	v_mfma_f32_16x16x32_bf16 v[96:99], v[160:163], v[238:241], v[96:99]
	v_mfma_f32_16x16x32_bf16 v[60:63], v[164:167], v[202:205], v[60:63]
	v_mfma_f32_16x16x32_bf16 v[56:59], v[172:175], v[202:205], v[56:59]
	v_mfma_f32_16x16x32_bf16 v[52:55], v[164:167], v[210:213], v[52:55]
	v_mfma_f32_16x16x32_bf16 v[48:51], v[172:175], v[210:213], v[48:51]
	v_mfma_f32_16x16x32_bf16 v[44:47], v[164:167], v[218:221], v[44:47]
	v_mfma_f32_16x16x32_bf16 v[40:43], v[172:175], v[218:221], v[40:43]
	v_mfma_f32_16x16x32_bf16 v[36:39], v[164:167], v[226:229], v[36:39]
	v_mfma_f32_16x16x32_bf16 v[32:35], v[172:175], v[226:229], v[32:35]
	v_mfma_f32_16x16x32_bf16 v[60:63], v[168:171], v[206:209], v[60:63]
	v_mfma_f32_16x16x32_bf16 v[56:59], v[198:201], v[206:209], v[56:59]
	v_mfma_f32_16x16x32_bf16 v[52:55], v[168:171], v[214:217], v[52:55]
	v_mfma_f32_16x16x32_bf16 v[48:51], v[198:201], v[214:217], v[48:51]
	v_mfma_f32_16x16x32_bf16 v[44:47], v[168:171], v[222:225], v[44:47]
	v_mfma_f32_16x16x32_bf16 v[40:43], v[198:201], v[222:225], v[40:43]
	v_mfma_f32_16x16x32_bf16 v[36:39], v[168:171], v[238:241], v[36:39]
	v_mfma_f32_16x16x32_bf16 v[32:35], v[198:201], v[238:241], v[32:35]
	s_barrier
	s_setprio 0
	s_add_i32 s30, s38, s5
	v_lshl_add_u64 v[138:139], v[138:139], 0, s[90:91]
	s_mov_b32 m0, s30
	ds_read_b128 v[202:205], v145 offset:49152
	ds_read_b128 v[206:209], v145 offset:50176
	ds_read_b128 v[210:213], v145 offset:51200
	ds_read_b128 v[214:217], v145 offset:52224
	ds_read_b128 v[218:221], v145 offset:53248
	ds_read_b128 v[222:225], v145 offset:54272
	ds_read_b128 v[226:229], v145 offset:55296
	ds_read_b128 v[238:241], v145 offset:56320
	global_load_lds_dwordx4 v[138:139], off
	s_add_i32 m0, s30, 0x2000
	s_add_u32 s30, s46, 0x40080
	v_lshl_add_u64 v[138:139], v[176:177], 0, s[90:91]
	s_addc_u32 s31, s47, 0
	s_add_i32 s38, s39, s5
	global_load_lds_dwordx4 v[138:139], off
	v_lshl_add_u64 v[138:139], s[30:31], 0, v[130:131]
	s_mov_b32 m0, s38
	s_nop 0
	global_load_lds_dwordx4 v[138:139], off
	v_lshl_add_u64 v[138:139], s[30:31], 0, v[132:133]
	s_add_i32 m0, s38, 0x2000
	s_nop 0
	global_load_lds_dwordx4 v[138:139], off
	v_lshl_add_u64 v[138:139], v[242:243], 0, s[90:91]
	s_mov_b32 m0, s55
	s_nop 0
	global_load_lds_dwordx4 v[138:139], off
	v_lshl_add_u64 v[138:139], v[244:245], 0, s[90:91]
	s_mov_b32 m0, s56
	s_nop 0
	global_load_lds_dwordx4 v[138:139], off
	s_waitcnt vmcnt(8)
	s_waitcnt lgkmcnt(0)
	s_setprio 1
	s_barrier
	v_mfma_f32_16x16x32_bf16 v[92:95], v[148:151], v[202:205], v[92:95]
	v_mfma_f32_16x16x32_bf16 v[88:91], v[156:159], v[202:205], v[88:91]
	v_mfma_f32_16x16x32_bf16 v[84:87], v[148:151], v[210:213], v[84:87]
	v_mfma_f32_16x16x32_bf16 v[80:83], v[156:159], v[210:213], v[80:83]
	v_mfma_f32_16x16x32_bf16 v[76:79], v[148:151], v[218:221], v[76:79]
	v_mfma_f32_16x16x32_bf16 v[72:75], v[156:159], v[218:221], v[72:75]
	v_mfma_f32_16x16x32_bf16 v[68:71], v[148:151], v[226:229], v[68:71]
	v_mfma_f32_16x16x32_bf16 v[64:67], v[156:159], v[226:229], v[64:67]
	v_mfma_f32_16x16x32_bf16 v[92:95], v[152:155], v[206:209], v[92:95]
	v_mfma_f32_16x16x32_bf16 v[88:91], v[160:163], v[206:209], v[88:91]
	v_mfma_f32_16x16x32_bf16 v[84:87], v[152:155], v[214:217], v[84:87]
	v_mfma_f32_16x16x32_bf16 v[80:83], v[160:163], v[214:217], v[80:83]
	v_mfma_f32_16x16x32_bf16 v[76:79], v[152:155], v[222:225], v[76:79]
	v_mfma_f32_16x16x32_bf16 v[72:75], v[160:163], v[222:225], v[72:75]
	v_mfma_f32_16x16x32_bf16 v[68:71], v[152:155], v[238:241], v[68:71]
	v_mfma_f32_16x16x32_bf16 v[64:67], v[160:163], v[238:241], v[64:67]
	v_mfma_f32_16x16x32_bf16 v[28:31], v[164:167], v[202:205], v[28:31]
	v_mfma_f32_16x16x32_bf16 v[24:27], v[172:175], v[202:205], v[24:27]
	v_mfma_f32_16x16x32_bf16 v[20:23], v[164:167], v[210:213], v[20:23]
	v_mfma_f32_16x16x32_bf16 v[16:19], v[172:175], v[210:213], v[16:19]
	v_mfma_f32_16x16x32_bf16 v[12:15], v[164:167], v[218:221], v[12:15]
	v_mfma_f32_16x16x32_bf16 v[8:11], v[172:175], v[218:221], v[8:11]
	v_mfma_f32_16x16x32_bf16 v[4:7], v[164:167], v[226:229], v[4:7]
	v_mfma_f32_16x16x32_bf16 v[0:3], v[172:175], v[226:229], v[0:3]
	v_mfma_f32_16x16x32_bf16 v[28:31], v[168:171], v[206:209], v[28:31]
	v_mfma_f32_16x16x32_bf16 v[24:27], v[198:201], v[206:209], v[24:27]
	v_mfma_f32_16x16x32_bf16 v[20:23], v[168:171], v[214:217], v[20:23]
	v_mfma_f32_16x16x32_bf16 v[16:19], v[198:201], v[214:217], v[16:19]
	v_mfma_f32_16x16x32_bf16 v[12:15], v[168:171], v[222:225], v[12:15]
	v_mfma_f32_16x16x32_bf16 v[8:11], v[198:201], v[222:225], v[8:11]
	v_mfma_f32_16x16x32_bf16 v[4:7], v[168:171], v[238:241], v[4:7]
	v_mfma_f32_16x16x32_bf16 v[0:3], v[198:201], v[238:241], v[0:3]
	s_barrier
	s_setprio 0
	s_add_i32 s73, s73, 2
	s_add_u32 s27, s27, 0x100
	s_addc_u32 s29, s29, 0
	s_cmp_gt_u32 s73, 13
	s_mov_b64 s[38:39], s[44:45]
	s_cbranch_scc0 .LBB0_224
	s_and_b64 vcc, exec, s[24:25]
	s_cbranch_vccz .LBB0_227
	s_barrier

.LBB0_273:
	s_add_u32 s30, s28, 0xfffc0080
	s_addc_u32 s31, s29, -1
	s_add_i32 s59, 0, 0x10000
	s_cmp_eq_u32 s58, 12
	s_cselect_b32 s45, s27, s31
	s_cselect_b32 s44, s53, s30
	v_add_u32_e32 v142, s59, v145
	s_cselect_b32 s35, s25, s57
	s_cselect_b32 s34, s55, s56
	s_add_i32 s60, 0, 0x14000
	ds_read_b128 v[146:149], v142
	ds_read_b128 v[150:153], v142 offset:1024
	ds_read_b128 v[154:157], v142 offset:2048
	ds_read_b128 v[158:161], v142 offset:3072
	v_add_u32_e32 v142, s60, v145
	ds_read_b128 v[162:165], v142
	ds_read_b128 v[166:169], v142 offset:1024
	ds_read_b128 v[170:173], v142 offset:2048
	ds_read_b128 v[174:177], v142 offset:3072
	v_lshl_add_u64 v[142:143], s[28:29], 0, v[138:139]
	s_add_i32 m0, s19, 0xc000
	ds_read_b128 v[198:201], v141
	ds_read_b128 v[202:205], v141 offset:1024
	ds_read_b128 v[206:209], v141 offset:2048
	ds_read_b128 v[210:213], v141 offset:3072
	ds_read_b128 v[214:217], v141 offset:4096
	ds_read_b128 v[218:221], v141 offset:5120
	ds_read_b128 v[222:225], v141 offset:6144
	ds_read_b128 v[226:229], v141 offset:7168
	global_load_lds_dwordx4 v[142:143], off
	v_lshl_add_u64 v[142:143], s[28:29], 0, v[136:137]
	s_add_i32 m0, s19, 0xe000
	s_nop 0
	global_load_lds_dwordx4 v[142:143], off
	s_waitcnt vmcnt(8)
	s_waitcnt lgkmcnt(0)
	s_setprio 1
	s_barrier
	v_mfma_f32_16x16x32_bf16 v[108:111], v[146:149], v[198:201], v[108:111]
	v_mfma_f32_16x16x32_bf16 v[116:119], v[154:157], v[198:201], v[116:119]
	v_mfma_f32_16x16x32_bf16 v[92:95], v[146:149], v[206:209], v[92:95]
	v_mfma_f32_16x16x32_bf16 v[100:103], v[154:157], v[206:209], v[100:103]
	v_mfma_f32_16x16x32_bf16 v[68:71], v[146:149], v[214:217], v[68:71]
	v_mfma_f32_16x16x32_bf16 v[76:79], v[154:157], v[214:217], v[76:79]
	v_mfma_f32_16x16x32_bf16 v[40:43], v[146:149], v[222:225], v[40:43]
	v_mfma_f32_16x16x32_bf16 v[44:47], v[154:157], v[222:225], v[44:47]
	v_mfma_f32_16x16x32_bf16 v[108:111], v[150:153], v[202:205], v[108:111]
	v_mfma_f32_16x16x32_bf16 v[116:119], v[158:161], v[202:205], v[116:119]
	v_mfma_f32_16x16x32_bf16 v[92:95], v[150:153], v[210:213], v[92:95]
	v_mfma_f32_16x16x32_bf16 v[100:103], v[158:161], v[210:213], v[100:103]
	v_mfma_f32_16x16x32_bf16 v[68:71], v[150:153], v[218:221], v[68:71]
	v_mfma_f32_16x16x32_bf16 v[76:79], v[158:161], v[218:221], v[76:79]
	v_mfma_f32_16x16x32_bf16 v[40:43], v[150:153], v[226:229], v[40:43]
	v_mfma_f32_16x16x32_bf16 v[44:47], v[158:161], v[226:229], v[44:47]
	v_mfma_f32_16x16x32_bf16 v[120:123], v[162:165], v[198:201], v[120:123]
	v_mfma_f32_16x16x32_bf16 v[124:127], v[170:173], v[198:201], v[124:127]
	v_mfma_f32_16x16x32_bf16 v[104:107], v[162:165], v[206:209], v[104:107]
	v_mfma_f32_16x16x32_bf16 v[112:115], v[170:173], v[206:209], v[112:115]
	v_mfma_f32_16x16x32_bf16 v[88:91], v[162:165], v[214:217], v[88:91]
	v_mfma_f32_16x16x32_bf16 v[96:99], v[170:173], v[214:217], v[96:99]
	v_mfma_f32_16x16x32_bf16 v[64:67], v[162:165], v[222:225], v[64:67]
	v_mfma_f32_16x16x32_bf16 v[72:75], v[170:173], v[222:225], v[72:75]
	v_mfma_f32_16x16x32_bf16 v[120:123], v[166:169], v[202:205], v[120:123]
	v_mfma_f32_16x16x32_bf16 v[124:127], v[174:177], v[202:205], v[124:127]
	v_mfma_f32_16x16x32_bf16 v[104:107], v[166:169], v[210:213], v[104:107]
	v_mfma_f32_16x16x32_bf16 v[112:115], v[174:177], v[210:213], v[112:115]
	v_mfma_f32_16x16x32_bf16 v[88:91], v[166:169], v[218:221], v[88:91]
	v_mfma_f32_16x16x32_bf16 v[96:99], v[174:177], v[218:221], v[96:99]
	v_mfma_f32_16x16x32_bf16 v[64:67], v[166:169], v[226:229], v[64:67]
	v_mfma_f32_16x16x32_bf16 v[72:75], v[174:177], v[226:229], v[72:75]
	s_barrier
	s_setprio 0
	s_add_i32 s30, s59, s4
	v_lshl_add_u64 v[142:143], s[34:35], 0, v[128:129]
	s_mov_b32 m0, s30
	ds_read_b128 v[198:201], v141 offset:16384
	ds_read_b128 v[202:205], v141 offset:17408
	ds_read_b128 v[206:209], v141 offset:18432
	ds_read_b128 v[210:213], v141 offset:19456
	ds_read_b128 v[214:217], v141 offset:20480
	ds_read_b128 v[218:221], v141 offset:21504
	ds_read_b128 v[222:225], v141 offset:22528
	ds_read_b128 v[226:229], v141 offset:23552
	global_load_lds_dwordx4 v[142:143], off
	s_add_i32 m0, s30, 0x2000
	s_add_u32 s30, s34, 0x40000
	v_lshl_add_u64 v[238:239], s[34:35], 0, v[130:131]
	s_addc_u32 s31, s35, 0
	s_add_i32 s59, s60, s4
	global_load_lds_dwordx4 v[238:239], off
	v_lshl_add_u64 v[240:241], s[30:31], 0, v[128:129]
	s_mov_b32 m0, s59
	v_lshl_add_u64 v[242:243], s[44:45], 0, v[132:133]
	global_load_lds_dwordx4 v[240:241], off
	v_lshl_add_u64 v[240:241], s[30:31], 0, v[130:131]
	s_add_i32 m0, s59, 0x2000
	s_nop 0
	global_load_lds_dwordx4 v[240:241], off
	v_lshl_add_u64 v[240:241], s[44:45], 0, v[134:135]
	s_mov_b32 m0, s19
	s_nop 0
	global_load_lds_dwordx4 v[240:241], off
	s_mov_b32 m0, s43
	s_nop 0
	global_load_lds_dwordx4 v[242:243], off
	s_waitcnt vmcnt(8)
	s_waitcnt lgkmcnt(0)
	s_setprio 1
	s_barrier
	v_mfma_f32_16x16x32_bf16 v[52:55], v[146:149], v[198:201], v[52:55]
	v_mfma_f32_16x16x32_bf16 v[60:63], v[154:157], v[198:201], v[60:63]
	v_mfma_f32_16x16x32_bf16 v[28:31], v[146:149], v[206:209], v[28:31]
	v_mfma_f32_16x16x32_bf16 v[36:39], v[154:157], v[206:209], v[36:39]
	v_mfma_f32_16x16x32_bf16 v[12:15], v[146:149], v[214:217], v[12:15]
	v_mfma_f32_16x16x32_bf16 v[16:19], v[154:157], v[214:217], v[16:19]
	v_mfma_f32_16x16x32_bf16 v[0:3], v[146:149], v[222:225], v[0:3]
	v_mfma_f32_16x16x32_bf16 v[4:7], v[154:157], v[222:225], v[4:7]
	v_mfma_f32_16x16x32_bf16 v[52:55], v[150:153], v[202:205], v[52:55]
	v_mfma_f32_16x16x32_bf16 v[60:63], v[158:161], v[202:205], v[60:63]
	v_mfma_f32_16x16x32_bf16 v[28:31], v[150:153], v[210:213], v[28:31]
	v_mfma_f32_16x16x32_bf16 v[36:39], v[158:161], v[210:213], v[36:39]
	v_mfma_f32_16x16x32_bf16 v[12:15], v[150:153], v[218:221], v[12:15]
	v_mfma_f32_16x16x32_bf16 v[16:19], v[158:161], v[218:221], v[16:19]
	v_mfma_f32_16x16x32_bf16 v[0:3], v[150:153], v[226:229], v[0:3]
	v_mfma_f32_16x16x32_bf16 v[4:7], v[158:161], v[226:229], v[4:7]
	v_mfma_f32_16x16x32_bf16 v[80:83], v[162:165], v[198:201], v[80:83]
	v_mfma_f32_16x16x32_bf16 v[84:87], v[170:173], v[198:201], v[84:87]
	v_mfma_f32_16x16x32_bf16 v[48:51], v[162:165], v[206:209], v[48:51]
	v_mfma_f32_16x16x32_bf16 v[56:59], v[170:173], v[206:209], v[56:59]
	v_mfma_f32_16x16x32_bf16 v[24:27], v[162:165], v[214:217], v[24:27]
	v_mfma_f32_16x16x32_bf16 v[32:35], v[170:173], v[214:217], v[32:35]
	v_mfma_f32_16x16x32_bf16 v[8:11], v[162:165], v[222:225], v[8:11]
	v_mfma_f32_16x16x32_bf16 v[20:23], v[170:173], v[222:225], v[20:23]
	v_mfma_f32_16x16x32_bf16 v[80:83], v[166:169], v[202:205], v[80:83]
	v_mfma_f32_16x16x32_bf16 v[84:87], v[174:177], v[202:205], v[84:87]
	v_mfma_f32_16x16x32_bf16 v[48:51], v[166:169], v[210:213], v[48:51]
	v_mfma_f32_16x16x32_bf16 v[56:59], v[174:177], v[210:213], v[56:59]
	v_mfma_f32_16x16x32_bf16 v[24:27], v[166:169], v[218:221], v[24:27]
	v_mfma_f32_16x16x32_bf16 v[32:35], v[174:177], v[218:221], v[32:35]
	v_mfma_f32_16x16x32_bf16 v[8:11], v[166:169], v[226:229], v[8:11]
	v_mfma_f32_16x16x32_bf16 v[20:23], v[174:177], v[226:229], v[20:23]
	s_barrier
	s_setprio 0
	s_add_i32 s59, 0, 0x18000
	s_add_i32 s60, 0, 0x1c000
	v_add_u32_e32 v158, s59, v145
	v_add_u32_e32 v174, s60, v145
	ds_read_b128 v[146:149], v158
	ds_read_b128 v[150:153], v158 offset:1024
	ds_read_b128 v[154:157], v158 offset:2048
	ds_read_b128 v[158:161], v158 offset:3072
	ds_read_b128 v[162:165], v174
	ds_read_b128 v[166:169], v174 offset:1024
	ds_read_b128 v[170:173], v174 offset:2048
	ds_read_b128 v[174:177], v174 offset:3072
	s_add_u32 s30, s44, 0x40000
	s_addc_u32 s31, s45, 0
	s_mov_b32 m0, s46
	v_lshl_add_u64 v[244:245], s[30:31], 0, v[134:135]
	ds_read_b128 v[198:201], v141 offset:32768
	ds_read_b128 v[202:205], v141 offset:33792
	ds_read_b128 v[206:209], v141 offset:34816
	ds_read_b128 v[210:213], v141 offset:35840
	ds_read_b128 v[214:217], v141 offset:36864
	ds_read_b128 v[218:221], v141 offset:37888
	ds_read_b128 v[222:225], v141 offset:38912
	ds_read_b128 v[226:229], v141 offset:39936
	global_load_lds_dwordx4 v[244:245], off
	v_lshl_add_u64 v[244:245], s[30:31], 0, v[132:133]
	s_mov_b32 m0, s47
	s_nop 0
	global_load_lds_dwordx4 v[244:245], off
	s_waitcnt vmcnt(8)
	s_waitcnt lgkmcnt(0)
	s_setprio 1
	s_barrier
	v_mfma_f32_16x16x32_bf16 v[108:111], v[146:149], v[198:201], v[108:111]
	v_mfma_f32_16x16x32_bf16 v[116:119], v[154:157], v[198:201], v[116:119]
	v_mfma_f32_16x16x32_bf16 v[92:95], v[146:149], v[206:209], v[92:95]
	v_mfma_f32_16x16x32_bf16 v[100:103], v[154:157], v[206:209], v[100:103]
	v_mfma_f32_16x16x32_bf16 v[68:71], v[146:149], v[214:217], v[68:71]
	v_mfma_f32_16x16x32_bf16 v[76:79], v[154:157], v[214:217], v[76:79]
	v_mfma_f32_16x16x32_bf16 v[40:43], v[146:149], v[222:225], v[40:43]
	v_mfma_f32_16x16x32_bf16 v[44:47], v[154:157], v[222:225], v[44:47]
	v_mfma_f32_16x16x32_bf16 v[108:111], v[150:153], v[202:205], v[108:111]
	v_mfma_f32_16x16x32_bf16 v[116:119], v[158:161], v[202:205], v[116:119]
	v_mfma_f32_16x16x32_bf16 v[92:95], v[150:153], v[210:213], v[92:95]
	v_mfma_f32_16x16x32_bf16 v[100:103], v[158:161], v[210:213], v[100:103]
	v_mfma_f32_16x16x32_bf16 v[68:71], v[150:153], v[218:221], v[68:71]
	v_mfma_f32_16x16x32_bf16 v[76:79], v[158:161], v[218:221], v[76:79]
	v_mfma_f32_16x16x32_bf16 v[40:43], v[150:153], v[226:229], v[40:43]
	v_mfma_f32_16x16x32_bf16 v[44:47], v[158:161], v[226:229], v[44:47]
	v_mfma_f32_16x16x32_bf16 v[120:123], v[162:165], v[198:201], v[120:123]
	v_mfma_f32_16x16x32_bf16 v[124:127], v[170:173], v[198:201], v[124:127]
	v_mfma_f32_16x16x32_bf16 v[104:107], v[162:165], v[206:209], v[104:107]
	v_mfma_f32_16x16x32_bf16 v[112:115], v[170:173], v[206:209], v[112:115]
	v_mfma_f32_16x16x32_bf16 v[88:91], v[162:165], v[214:217], v[88:91]
	v_mfma_f32_16x16x32_bf16 v[96:99], v[170:173], v[214:217], v[96:99]
	v_mfma_f32_16x16x32_bf16 v[64:67], v[162:165], v[222:225], v[64:67]
	v_mfma_f32_16x16x32_bf16 v[72:75], v[170:173], v[222:225], v[72:75]
	v_mfma_f32_16x16x32_bf16 v[120:123], v[166:169], v[202:205], v[120:123]
	v_mfma_f32_16x16x32_bf16 v[124:127], v[174:177], v[202:205], v[124:127]
	v_mfma_f32_16x16x32_bf16 v[104:107], v[166:169], v[210:213], v[104:107]
	v_mfma_f32_16x16x32_bf16 v[112:115], v[174:177], v[210:213], v[112:115]
	v_mfma_f32_16x16x32_bf16 v[88:91], v[166:169], v[218:221], v[88:91]
	v_mfma_f32_16x16x32_bf16 v[96:99], v[174:177], v[218:221], v[96:99]
	v_mfma_f32_16x16x32_bf16 v[64:67], v[166:169], v[226:229], v[64:67]
	v_mfma_f32_16x16x32_bf16 v[72:75], v[174:177], v[226:229], v[72:75]
	s_barrier
	s_setprio 0
	s_add_i32 s30, s59, s4
	v_lshl_add_u64 v[142:143], v[142:143], 0, s[90:91]
	s_mov_b32 m0, s30
	ds_read_b128 v[198:201], v141 offset:49152
	ds_read_b128 v[202:205], v141 offset:50176
	ds_read_b128 v[206:209], v141 offset:51200
	ds_read_b128 v[210:213], v141 offset:52224
	ds_read_b128 v[214:217], v141 offset:53248
	ds_read_b128 v[218:221], v141 offset:54272
	ds_read_b128 v[222:225], v141 offset:55296
	ds_read_b128 v[226:229], v141 offset:56320
	global_load_lds_dwordx4 v[142:143], off
	s_add_i32 m0, s30, 0x2000
	s_add_u32 s30, s34, 0x40080
	v_lshl_add_u64 v[142:143], v[238:239], 0, s[90:91]
	s_addc_u32 s31, s35, 0
	s_add_i32 s34, s60, s4
	global_load_lds_dwordx4 v[142:143], off
	v_lshl_add_u64 v[142:143], s[30:31], 0, v[128:129]
	s_mov_b32 m0, s34
	s_nop 0
	global_load_lds_dwordx4 v[142:143], off
	v_lshl_add_u64 v[142:143], s[30:31], 0, v[130:131]
	s_add_i32 m0, s34, 0x2000
	s_nop 0
	global_load_lds_dwordx4 v[142:143], off
	v_lshl_add_u64 v[142:143], v[240:241], 0, s[90:91]
	s_mov_b32 m0, s21
	s_nop 0
	global_load_lds_dwordx4 v[142:143], off
	v_lshl_add_u64 v[142:143], v[242:243], 0, s[90:91]
	s_mov_b32 m0, s48
	s_nop 0
	global_load_lds_dwordx4 v[142:143], off
	s_waitcnt vmcnt(8)
	s_waitcnt lgkmcnt(0)
	s_setprio 1
	s_barrier
	v_mfma_f32_16x16x32_bf16 v[52:55], v[146:149], v[198:201], v[52:55]
	v_mfma_f32_16x16x32_bf16 v[60:63], v[154:157], v[198:201], v[60:63]
	v_mfma_f32_16x16x32_bf16 v[28:31], v[146:149], v[206:209], v[28:31]
	v_mfma_f32_16x16x32_bf16 v[36:39], v[154:157], v[206:209], v[36:39]
	v_mfma_f32_16x16x32_bf16 v[12:15], v[146:149], v[214:217], v[12:15]
	v_mfma_f32_16x16x32_bf16 v[16:19], v[154:157], v[214:217], v[16:19]
	v_mfma_f32_16x16x32_bf16 v[0:3], v[146:149], v[222:225], v[0:3]
	v_mfma_f32_16x16x32_bf16 v[4:7], v[154:157], v[222:225], v[4:7]
	v_mfma_f32_16x16x32_bf16 v[52:55], v[150:153], v[202:205], v[52:55]
	v_mfma_f32_16x16x32_bf16 v[60:63], v[158:161], v[202:205], v[60:63]
	v_mfma_f32_16x16x32_bf16 v[28:31], v[150:153], v[210:213], v[28:31]
	v_mfma_f32_16x16x32_bf16 v[36:39], v[158:161], v[210:213], v[36:39]
	v_mfma_f32_16x16x32_bf16 v[12:15], v[150:153], v[218:221], v[12:15]
	v_mfma_f32_16x16x32_bf16 v[16:19], v[158:161], v[218:221], v[16:19]
	v_mfma_f32_16x16x32_bf16 v[0:3], v[150:153], v[226:229], v[0:3]
	v_mfma_f32_16x16x32_bf16 v[4:7], v[158:161], v[226:229], v[4:7]
	v_mfma_f32_16x16x32_bf16 v[80:83], v[162:165], v[198:201], v[80:83]
	v_mfma_f32_16x16x32_bf16 v[84:87], v[170:173], v[198:201], v[84:87]
	v_mfma_f32_16x16x32_bf16 v[48:51], v[162:165], v[206:209], v[48:51]
	v_mfma_f32_16x16x32_bf16 v[56:59], v[170:173], v[206:209], v[56:59]
	v_mfma_f32_16x16x32_bf16 v[24:27], v[162:165], v[214:217], v[24:27]
	v_mfma_f32_16x16x32_bf16 v[32:35], v[170:173], v[214:217], v[32:35]
	v_mfma_f32_16x16x32_bf16 v[8:11], v[162:165], v[222:225], v[8:11]
	v_mfma_f32_16x16x32_bf16 v[20:23], v[170:173], v[222:225], v[20:23]
	v_mfma_f32_16x16x32_bf16 v[80:83], v[166:169], v[202:205], v[80:83]
	v_mfma_f32_16x16x32_bf16 v[84:87], v[174:177], v[202:205], v[84:87]
	v_mfma_f32_16x16x32_bf16 v[48:51], v[166:169], v[210:213], v[48:51]
	v_mfma_f32_16x16x32_bf16 v[56:59], v[174:177], v[210:213], v[56:59]
	v_mfma_f32_16x16x32_bf16 v[24:27], v[166:169], v[218:221], v[24:27]
	v_mfma_f32_16x16x32_bf16 v[32:35], v[174:177], v[218:221], v[32:35]
	v_mfma_f32_16x16x32_bf16 v[8:11], v[166:169], v[226:229], v[8:11]
	v_mfma_f32_16x16x32_bf16 v[20:23], v[174:177], v[226:229], v[20:23]
	s_barrier
	s_setprio 0
	s_add_i32 s58, s58, 2
	s_add_u32 s56, s56, 0x100
	s_addc_u32 s57, s57, 0
	s_add_u32 s28, s28, 0x100
	s_addc_u32 s29, s29, 0
	s_cmp_gt_u32 s58, 13
	s_cbranch_scc0 .LBB0_273
	s_and_b64 vcc, exec, s[16:17]
	s_cbranch_vccz .LBB0_276
	s_barrier

.LBB0_296:
	s_add_u32 s8, s10, 0x100
	s_addc_u32 s9, s11, 0
	s_add_i32 s30, 0, 0x10000
	s_cmp_eq_u32 s55, 2
	s_cselect_b32 s37, s27, s9
	s_cselect_b32 s36, s26, s8
	v_add_u32_e32 v138, s30, v141
	s_cselect_b32 s35, s29, s53
	s_cselect_b32 s34, s28, s52
	s_add_i32 s31, 0, 0x14000
	ds_read_b128 v[148:151], v138
	ds_read_b128 v[152:155], v138 offset:1024
	ds_read_b128 v[156:159], v138 offset:2048
	ds_read_b128 v[160:163], v138 offset:3072
	v_add_u32_e32 v138, s31, v141
	ds_read_b128 v[164:167], v138
	ds_read_b128 v[168:171], v138 offset:1024
	ds_read_b128 v[172:175], v138 offset:2048
	ds_read_b128 v[198:201], v138 offset:3072
	v_lshl_add_u64 v[138:139], s[10:11], 0, v[136:137]
	s_add_i32 m0, s39, 0xc000
	ds_read_b128 v[202:205], v145
	ds_read_b128 v[206:209], v145 offset:1024
	ds_read_b128 v[210:213], v145 offset:2048
	ds_read_b128 v[214:217], v145 offset:3072
	ds_read_b128 v[218:221], v145 offset:4096
	ds_read_b128 v[222:225], v145 offset:5120
	ds_read_b128 v[226:229], v145 offset:6144
	ds_read_b128 v[238:241], v145 offset:7168
	global_load_lds_dwordx4 v[138:139], off
	v_lshl_add_u64 v[138:139], s[10:11], 0, v[134:135]
	s_add_i32 m0, s39, 0xe000
	s_nop 0
	global_load_lds_dwordx4 v[138:139], off
	s_waitcnt vmcnt(8)
	s_waitcnt lgkmcnt(0)
	s_setprio 1
	s_barrier
	v_mfma_f32_16x16x32_bf16 v[124:127], v[148:151], v[202:205], v[124:127]
	v_mfma_f32_16x16x32_bf16 v[120:123], v[156:159], v[202:205], v[120:123]
	v_mfma_f32_16x16x32_bf16 v[116:119], v[148:151], v[210:213], v[116:119]
	v_mfma_f32_16x16x32_bf16 v[112:115], v[156:159], v[210:213], v[112:115]
	v_mfma_f32_16x16x32_bf16 v[108:111], v[148:151], v[218:221], v[108:111]
	v_mfma_f32_16x16x32_bf16 v[104:107], v[156:159], v[218:221], v[104:107]
	v_mfma_f32_16x16x32_bf16 v[100:103], v[148:151], v[226:229], v[100:103]
	v_mfma_f32_16x16x32_bf16 v[96:99], v[156:159], v[226:229], v[96:99]
	v_mfma_f32_16x16x32_bf16 v[124:127], v[152:155], v[206:209], v[124:127]
	v_mfma_f32_16x16x32_bf16 v[120:123], v[160:163], v[206:209], v[120:123]
	v_mfma_f32_16x16x32_bf16 v[116:119], v[152:155], v[214:217], v[116:119]
	v_mfma_f32_16x16x32_bf16 v[112:115], v[160:163], v[214:217], v[112:115]
	v_mfma_f32_16x16x32_bf16 v[108:111], v[152:155], v[222:225], v[108:111]
	v_mfma_f32_16x16x32_bf16 v[104:107], v[160:163], v[222:225], v[104:107]
	v_mfma_f32_16x16x32_bf16 v[100:103], v[152:155], v[238:241], v[100:103]
	v_mfma_f32_16x16x32_bf16 v[96:99], v[160:163], v[238:241], v[96:99]
	v_mfma_f32_16x16x32_bf16 v[60:63], v[164:167], v[202:205], v[60:63]
	v_mfma_f32_16x16x32_bf16 v[56:59], v[172:175], v[202:205], v[56:59]
	v_mfma_f32_16x16x32_bf16 v[52:55], v[164:167], v[210:213], v[52:55]
	v_mfma_f32_16x16x32_bf16 v[48:51], v[172:175], v[210:213], v[48:51]
	v_mfma_f32_16x16x32_bf16 v[44:47], v[164:167], v[218:221], v[44:47]
	v_mfma_f32_16x16x32_bf16 v[40:43], v[172:175], v[218:221], v[40:43]
	v_mfma_f32_16x16x32_bf16 v[36:39], v[164:167], v[226:229], v[36:39]
	v_mfma_f32_16x16x32_bf16 v[32:35], v[172:175], v[226:229], v[32:35]
	v_mfma_f32_16x16x32_bf16 v[60:63], v[168:171], v[206:209], v[60:63]
	v_mfma_f32_16x16x32_bf16 v[56:59], v[198:201], v[206:209], v[56:59]
	v_mfma_f32_16x16x32_bf16 v[52:55], v[168:171], v[214:217], v[52:55]
	v_mfma_f32_16x16x32_bf16 v[48:51], v[198:201], v[214:217], v[48:51]
	v_mfma_f32_16x16x32_bf16 v[44:47], v[168:171], v[222:225], v[44:47]
	v_mfma_f32_16x16x32_bf16 v[40:43], v[198:201], v[222:225], v[40:43]
	v_mfma_f32_16x16x32_bf16 v[36:39], v[168:171], v[238:241], v[36:39]
	v_mfma_f32_16x16x32_bf16 v[32:35], v[198:201], v[238:241], v[32:35]
	s_barrier
	s_setprio 0
	s_add_i32 s10, s30, s38
	v_lshl_add_u64 v[138:139], s[34:35], 0, v[130:131]
	s_mov_b32 m0, s10
	ds_read_b128 v[202:205], v145 offset:16384
	ds_read_b128 v[206:209], v145 offset:17408
	ds_read_b128 v[210:213], v145 offset:18432
	ds_read_b128 v[214:217], v145 offset:19456
	ds_read_b128 v[218:221], v145 offset:20480
	ds_read_b128 v[222:225], v145 offset:21504
	ds_read_b128 v[226:229], v145 offset:22528
	ds_read_b128 v[238:241], v145 offset:23552
	global_load_lds_dwordx4 v[138:139], off
	s_add_i32 m0, s10, 0x2000
	s_add_u32 s10, s34, 0x18000
	v_lshl_add_u64 v[176:177], s[34:35], 0, v[132:133]
	s_addc_u32 s11, s35, 0
	s_add_i32 s30, s31, s38
	global_load_lds_dwordx4 v[176:177], off
	v_lshl_add_u64 v[242:243], s[10:11], 0, v[130:131]
	s_mov_b32 m0, s30
	v_lshl_add_u64 v[244:245], s[36:37], 0, v[132:133]
	global_load_lds_dwordx4 v[242:243], off
	v_lshl_add_u64 v[242:243], s[10:11], 0, v[132:133]
	s_add_i32 m0, s30, 0x2000
	s_nop 0
	global_load_lds_dwordx4 v[242:243], off
	v_lshl_add_u64 v[242:243], s[36:37], 0, v[130:131]
	s_mov_b32 m0, s39
	s_nop 0
	global_load_lds_dwordx4 v[242:243], off
	s_mov_b32 m0, s40
	s_nop 0
	global_load_lds_dwordx4 v[244:245], off
	s_waitcnt vmcnt(8)
	s_waitcnt lgkmcnt(0)
	s_setprio 1
	s_barrier
	v_mfma_f32_16x16x32_bf16 v[92:95], v[148:151], v[202:205], v[92:95]
	v_mfma_f32_16x16x32_bf16 v[88:91], v[156:159], v[202:205], v[88:91]
	v_mfma_f32_16x16x32_bf16 v[84:87], v[148:151], v[210:213], v[84:87]
	v_mfma_f32_16x16x32_bf16 v[80:83], v[156:159], v[210:213], v[80:83]
	v_mfma_f32_16x16x32_bf16 v[76:79], v[148:151], v[218:221], v[76:79]
	v_mfma_f32_16x16x32_bf16 v[72:75], v[156:159], v[218:221], v[72:75]
	v_mfma_f32_16x16x32_bf16 v[68:71], v[148:151], v[226:229], v[68:71]
	v_mfma_f32_16x16x32_bf16 v[64:67], v[156:159], v[226:229], v[64:67]
	v_mfma_f32_16x16x32_bf16 v[92:95], v[152:155], v[206:209], v[92:95]
	v_mfma_f32_16x16x32_bf16 v[88:91], v[160:163], v[206:209], v[88:91]
	v_mfma_f32_16x16x32_bf16 v[84:87], v[152:155], v[214:217], v[84:87]
	v_mfma_f32_16x16x32_bf16 v[80:83], v[160:163], v[214:217], v[80:83]
	v_mfma_f32_16x16x32_bf16 v[76:79], v[152:155], v[222:225], v[76:79]
	v_mfma_f32_16x16x32_bf16 v[72:75], v[160:163], v[222:225], v[72:75]
	v_mfma_f32_16x16x32_bf16 v[68:71], v[152:155], v[238:241], v[68:71]
	v_mfma_f32_16x16x32_bf16 v[64:67], v[160:163], v[238:241], v[64:67]
	v_mfma_f32_16x16x32_bf16 v[28:31], v[164:167], v[202:205], v[28:31]
	v_mfma_f32_16x16x32_bf16 v[24:27], v[172:175], v[202:205], v[24:27]
	v_mfma_f32_16x16x32_bf16 v[20:23], v[164:167], v[210:213], v[20:23]
	v_mfma_f32_16x16x32_bf16 v[16:19], v[172:175], v[210:213], v[16:19]
	v_mfma_f32_16x16x32_bf16 v[12:15], v[164:167], v[218:221], v[12:15]
	v_mfma_f32_16x16x32_bf16 v[8:11], v[172:175], v[218:221], v[8:11]
	v_mfma_f32_16x16x32_bf16 v[4:7], v[164:167], v[226:229], v[4:7]
	v_mfma_f32_16x16x32_bf16 v[0:3], v[172:175], v[226:229], v[0:3]
	v_mfma_f32_16x16x32_bf16 v[28:31], v[168:171], v[206:209], v[28:31]
	v_mfma_f32_16x16x32_bf16 v[24:27], v[198:201], v[206:209], v[24:27]
	v_mfma_f32_16x16x32_bf16 v[20:23], v[168:171], v[214:217], v[20:23]
	v_mfma_f32_16x16x32_bf16 v[16:19], v[198:201], v[214:217], v[16:19]
	v_mfma_f32_16x16x32_bf16 v[12:15], v[168:171], v[222:225], v[12:15]
	v_mfma_f32_16x16x32_bf16 v[8:11], v[198:201], v[222:225], v[8:11]
	v_mfma_f32_16x16x32_bf16 v[4:7], v[168:171], v[238:241], v[4:7]
	v_mfma_f32_16x16x32_bf16 v[0:3], v[198:201], v[238:241], v[0:3]
	s_barrier
	s_setprio 0
	s_add_i32 s30, 0, 0x18000
	v_add_u32_e32 v147, s30, v141
	s_add_i32 s31, 0, 0x1c000
	ds_read_b128 v[148:151], v147
	ds_read_b128 v[152:155], v147 offset:1024
	ds_read_b128 v[156:159], v147 offset:2048
	ds_read_b128 v[160:163], v147 offset:3072
	v_add_u32_e32 v147, s31, v141
	ds_read_b128 v[164:167], v147
	ds_read_b128 v[168:171], v147 offset:1024
	ds_read_b128 v[172:175], v147 offset:2048
	ds_read_b128 v[198:201], v147 offset:3072
	s_add_u32 s10, s36, 0x18000
	s_addc_u32 s11, s37, 0
	s_mov_b32 m0, s41
	v_lshl_add_u64 v[246:247], s[10:11], 0, v[130:131]
	ds_read_b128 v[202:205], v145 offset:32768
	ds_read_b128 v[206:209], v145 offset:33792
	ds_read_b128 v[210:213], v145 offset:34816
	ds_read_b128 v[214:217], v145 offset:35840
	ds_read_b128 v[218:221], v145 offset:36864
	ds_read_b128 v[222:225], v145 offset:37888
	ds_read_b128 v[226:229], v145 offset:38912
	ds_read_b128 v[238:241], v145 offset:39936
	global_load_lds_dwordx4 v[246:247], off
	v_lshl_add_u64 v[246:247], s[10:11], 0, v[132:133]
	s_mov_b32 m0, s42
	s_nop 0
	global_load_lds_dwordx4 v[246:247], off
	s_waitcnt vmcnt(8)
	s_waitcnt lgkmcnt(0)
	s_setprio 1
	s_barrier
	v_mfma_f32_16x16x32_bf16 v[124:127], v[148:151], v[202:205], v[124:127]
	v_mfma_f32_16x16x32_bf16 v[120:123], v[156:159], v[202:205], v[120:123]
	v_mfma_f32_16x16x32_bf16 v[116:119], v[148:151], v[210:213], v[116:119]
	v_mfma_f32_16x16x32_bf16 v[112:115], v[156:159], v[210:213], v[112:115]
	v_mfma_f32_16x16x32_bf16 v[108:111], v[148:151], v[218:221], v[108:111]
	v_mfma_f32_16x16x32_bf16 v[104:107], v[156:159], v[218:221], v[104:107]
	v_mfma_f32_16x16x32_bf16 v[100:103], v[148:151], v[226:229], v[100:103]
	v_mfma_f32_16x16x32_bf16 v[96:99], v[156:159], v[226:229], v[96:99]
	v_mfma_f32_16x16x32_bf16 v[124:127], v[152:155], v[206:209], v[124:127]
	v_mfma_f32_16x16x32_bf16 v[120:123], v[160:163], v[206:209], v[120:123]
	v_mfma_f32_16x16x32_bf16 v[116:119], v[152:155], v[214:217], v[116:119]
	v_mfma_f32_16x16x32_bf16 v[112:115], v[160:163], v[214:217], v[112:115]
	v_mfma_f32_16x16x32_bf16 v[108:111], v[152:155], v[222:225], v[108:111]
	v_mfma_f32_16x16x32_bf16 v[104:107], v[160:163], v[222:225], v[104:107]
	v_mfma_f32_16x16x32_bf16 v[100:103], v[152:155], v[238:241], v[100:103]
	v_mfma_f32_16x16x32_bf16 v[96:99], v[160:163], v[238:241], v[96:99]
	v_mfma_f32_16x16x32_bf16 v[60:63], v[164:167], v[202:205], v[60:63]
	v_mfma_f32_16x16x32_bf16 v[56:59], v[172:175], v[202:205], v[56:59]
	v_mfma_f32_16x16x32_bf16 v[52:55], v[164:167], v[210:213], v[52:55]
	v_mfma_f32_16x16x32_bf16 v[48:51], v[172:175], v[210:213], v[48:51]
	v_mfma_f32_16x16x32_bf16 v[44:47], v[164:167], v[218:221], v[44:47]
	v_mfma_f32_16x16x32_bf16 v[40:43], v[172:175], v[218:221], v[40:43]
	v_mfma_f32_16x16x32_bf16 v[36:39], v[164:167], v[226:229], v[36:39]
	v_mfma_f32_16x16x32_bf16 v[32:35], v[172:175], v[226:229], v[32:35]
	v_mfma_f32_16x16x32_bf16 v[60:63], v[168:171], v[206:209], v[60:63]
	v_mfma_f32_16x16x32_bf16 v[56:59], v[198:201], v[206:209], v[56:59]
	v_mfma_f32_16x16x32_bf16 v[52:55], v[168:171], v[214:217], v[52:55]
	v_mfma_f32_16x16x32_bf16 v[48:51], v[198:201], v[214:217], v[48:51]
	v_mfma_f32_16x16x32_bf16 v[44:47], v[168:171], v[222:225], v[44:47]
	v_mfma_f32_16x16x32_bf16 v[40:43], v[198:201], v[222:225], v[40:43]
	v_mfma_f32_16x16x32_bf16 v[36:39], v[168:171], v[238:241], v[36:39]
	v_mfma_f32_16x16x32_bf16 v[32:35], v[198:201], v[238:241], v[32:35]
	s_barrier
	s_setprio 0
	s_add_i32 s10, s30, s38
	v_lshl_add_u64 v[138:139], v[138:139], 0, s[90:91]
	s_mov_b32 m0, s10
	ds_read_b128 v[202:205], v145 offset:49152
	ds_read_b128 v[206:209], v145 offset:50176
	ds_read_b128 v[210:213], v145 offset:51200
	ds_read_b128 v[214:217], v145 offset:52224
	ds_read_b128 v[218:221], v145 offset:53248
	ds_read_b128 v[222:225], v145 offset:54272
	ds_read_b128 v[226:229], v145 offset:55296
	ds_read_b128 v[238:241], v145 offset:56320
	global_load_lds_dwordx4 v[138:139], off
	s_add_i32 m0, s10, 0x2000
	s_add_u32 s10, s34, 0x18080
	v_lshl_add_u64 v[138:139], v[176:177], 0, s[90:91]
	s_addc_u32 s11, s35, 0
	s_add_i32 s30, s31, s38
	global_load_lds_dwordx4 v[138:139], off
	v_lshl_add_u64 v[138:139], s[10:11], 0, v[130:131]
	s_mov_b32 m0, s30
	s_nop 0
	global_load_lds_dwordx4 v[138:139], off
	v_lshl_add_u64 v[138:139], s[10:11], 0, v[132:133]
	s_add_i32 m0, s30, 0x2000
	s_nop 0
	global_load_lds_dwordx4 v[138:139], off
	v_lshl_add_u64 v[138:139], v[242:243], 0, s[90:91]
	s_mov_b32 m0, s45
	s_nop 0
	global_load_lds_dwordx4 v[138:139], off
	v_lshl_add_u64 v[138:139], v[244:245], 0, s[90:91]
	s_mov_b32 m0, s46
	s_nop 0
	global_load_lds_dwordx4 v[138:139], off
	s_waitcnt vmcnt(8)
	s_waitcnt lgkmcnt(0)
	s_setprio 1
	s_barrier
	v_mfma_f32_16x16x32_bf16 v[92:95], v[148:151], v[202:205], v[92:95]
	v_mfma_f32_16x16x32_bf16 v[88:91], v[156:159], v[202:205], v[88:91]
	v_mfma_f32_16x16x32_bf16 v[84:87], v[148:151], v[210:213], v[84:87]
	v_mfma_f32_16x16x32_bf16 v[80:83], v[156:159], v[210:213], v[80:83]
	v_mfma_f32_16x16x32_bf16 v[76:79], v[148:151], v[218:221], v[76:79]
	v_mfma_f32_16x16x32_bf16 v[72:75], v[156:159], v[218:221], v[72:75]
	v_mfma_f32_16x16x32_bf16 v[68:71], v[148:151], v[226:229], v[68:71]
	v_mfma_f32_16x16x32_bf16 v[64:67], v[156:159], v[226:229], v[64:67]
	v_mfma_f32_16x16x32_bf16 v[92:95], v[152:155], v[206:209], v[92:95]
	v_mfma_f32_16x16x32_bf16 v[88:91], v[160:163], v[206:209], v[88:91]
	v_mfma_f32_16x16x32_bf16 v[84:87], v[152:155], v[214:217], v[84:87]
	v_mfma_f32_16x16x32_bf16 v[80:83], v[160:163], v[214:217], v[80:83]
	v_mfma_f32_16x16x32_bf16 v[76:79], v[152:155], v[222:225], v[76:79]
	v_mfma_f32_16x16x32_bf16 v[72:75], v[160:163], v[222:225], v[72:75]
	v_mfma_f32_16x16x32_bf16 v[68:71], v[152:155], v[238:241], v[68:71]
	v_mfma_f32_16x16x32_bf16 v[64:67], v[160:163], v[238:241], v[64:67]
	v_mfma_f32_16x16x32_bf16 v[28:31], v[164:167], v[202:205], v[28:31]
	v_mfma_f32_16x16x32_bf16 v[24:27], v[172:175], v[202:205], v[24:27]
	v_mfma_f32_16x16x32_bf16 v[20:23], v[164:167], v[210:213], v[20:23]
	v_mfma_f32_16x16x32_bf16 v[16:19], v[172:175], v[210:213], v[16:19]
	v_mfma_f32_16x16x32_bf16 v[12:15], v[164:167], v[218:221], v[12:15]
	v_mfma_f32_16x16x32_bf16 v[8:11], v[172:175], v[218:221], v[8:11]
	v_mfma_f32_16x16x32_bf16 v[4:7], v[164:167], v[226:229], v[4:7]
	v_mfma_f32_16x16x32_bf16 v[0:3], v[172:175], v[226:229], v[0:3]
	v_mfma_f32_16x16x32_bf16 v[28:31], v[168:171], v[206:209], v[28:31]
	v_mfma_f32_16x16x32_bf16 v[24:27], v[198:201], v[206:209], v[24:27]
	v_mfma_f32_16x16x32_bf16 v[20:23], v[168:171], v[214:217], v[20:23]
	v_mfma_f32_16x16x32_bf16 v[16:19], v[198:201], v[214:217], v[16:19]
	v_mfma_f32_16x16x32_bf16 v[12:15], v[168:171], v[222:225], v[12:15]
	v_mfma_f32_16x16x32_bf16 v[8:11], v[198:201], v[222:225], v[8:11]
	v_mfma_f32_16x16x32_bf16 v[4:7], v[168:171], v[238:241], v[4:7]
	v_mfma_f32_16x16x32_bf16 v[0:3], v[198:201], v[238:241], v[0:3]
	s_barrier
	s_setprio 0
	s_add_i32 s55, s55, 2
	s_add_u32 s52, s52, 0x100
	s_addc_u32 s53, s53, 0
	s_cmp_gt_u32 s55, 3
	s_mov_b64 s[10:11], s[8:9]
	s_cbranch_scc0 .LBB0_296
	s_and_b64 vcc, exec, s[24:25]
	s_cbranch_vccz .LBB0_299
	s_barrier

.LBB0_344:
	s_add_u32 s47, s34, s46
	s_addc_u32 s59, s35, 0
	s_add_u32 s48, s47, 0x100
	s_addc_u32 s49, s59, 0
	s_and_b64 s[30:31], s[44:45], exec
	s_cselect_b32 s49, s19, s49
	s_cselect_b32 s48, s57, s48
	s_add_u32 s30, s36, s46
	s_addc_u32 s31, s37, 0
	s_add_u32 s46, s30, 0x100
	s_addc_u32 s50, s31, 0
	s_add_i32 s74, 0, 0x10000
	s_and_b64 s[30:31], s[44:45], exec
	s_cselect_b32 s51, s17, s50
	s_cselect_b32 s50, s58, s46
	s_add_i32 s45, 0, 0x14000
	s_add_u32 s30, s47, 0x10080
	s_addc_u32 s31, s59, 0
	s_add_i32 s83, s74, s40
	s_add_i32 m0, s20, 0xc000
	s_add_i32 s82, s20, 0xe000
	s_add_i32 s84, s83, 0x2000
	s_add_u32 s60, s50, 0x10000
	v_add_u32_e32 v152, s74, v137
	v_add_u32_e32 v168, s45, v137
	s_addc_u32 s61, s51, 0
	s_add_i32 s85, s45, s40
	ds_read_b128 v[140:143], v152
	ds_read_b128 v[144:147], v152 offset:1024
	ds_read_b128 v[148:151], v152 offset:2048
	ds_read_b128 v[152:155], v152 offset:3072
	ds_read_b128 v[156:159], v168
	ds_read_b128 v[160:163], v168 offset:1024
	ds_read_b128 v[164:167], v168 offset:2048
	ds_read_b128 v[168:171], v168 offset:3072
	s_add_i32 s86, s85, 0x2000
	s_add_i32 s87, 0, 0x18000
	s_add_i32 s88, 0, 0x1c000
	s_add_u32 s46, s48, 0x10000
	s_addc_u32 s47, s49, 0
	s_add_i32 s73, s87, s40
	s_add_i32 s59, s73, 0x2000
	s_add_u32 s44, s50, 0x10080
	s_addc_u32 s45, s51, 0
	s_add_i32 s81, s88, s40
	s_add_i32 s74, s81, 0x2000
	v_lshl_add_u64 v[176:177], s[30:31], 0, v[134:135]
	ds_read_b128 v[172:175], v139
	ds_read_b128 v[198:201], v139 offset:1024
	ds_read_b128 v[202:205], v139 offset:2048
	ds_read_b128 v[206:209], v139 offset:3072
	ds_read_b128 v[210:213], v139 offset:4096
	ds_read_b128 v[214:217], v139 offset:5120
	ds_read_b128 v[218:221], v139 offset:6144
	ds_read_b128 v[222:225], v139 offset:7168
	global_load_lds_dwordx4 v[176:177], off
	v_lshl_add_u64 v[176:177], s[30:31], 0, v[132:133]
	s_mov_b32 m0, s82
	s_nop 0
	global_load_lds_dwordx4 v[176:177], off
	s_waitcnt vmcnt(8)
	s_waitcnt lgkmcnt(0)
	s_setprio 1
	s_barrier
	v_mfma_f32_16x16x32_bf16 v[112:115], v[140:143], v[172:175], v[112:115]
	v_mfma_f32_16x16x32_bf16 v[116:119], v[148:151], v[172:175], v[116:119]
	v_mfma_f32_16x16x32_bf16 v[96:99], v[140:143], v[202:205], v[96:99]
	v_mfma_f32_16x16x32_bf16 v[100:103], v[148:151], v[202:205], v[100:103]
	v_mfma_f32_16x16x32_bf16 v[72:75], v[140:143], v[210:213], v[72:75]
	v_mfma_f32_16x16x32_bf16 v[80:83], v[148:151], v[210:213], v[80:83]
	v_mfma_f32_16x16x32_bf16 v[40:43], v[140:143], v[218:221], v[40:43]
	v_mfma_f32_16x16x32_bf16 v[48:51], v[148:151], v[218:221], v[48:51]
	v_mfma_f32_16x16x32_bf16 v[112:115], v[144:147], v[198:201], v[112:115]
	v_mfma_f32_16x16x32_bf16 v[116:119], v[152:155], v[198:201], v[116:119]
	v_mfma_f32_16x16x32_bf16 v[96:99], v[144:147], v[206:209], v[96:99]
	v_mfma_f32_16x16x32_bf16 v[100:103], v[152:155], v[206:209], v[100:103]
	v_mfma_f32_16x16x32_bf16 v[72:75], v[144:147], v[214:217], v[72:75]
	v_mfma_f32_16x16x32_bf16 v[80:83], v[152:155], v[214:217], v[80:83]
	v_mfma_f32_16x16x32_bf16 v[40:43], v[144:147], v[222:225], v[40:43]
	v_mfma_f32_16x16x32_bf16 v[48:51], v[152:155], v[222:225], v[48:51]
	v_mfma_f32_16x16x32_bf16 v[120:123], v[156:159], v[172:175], v[120:123]
	v_mfma_f32_16x16x32_bf16 v[124:127], v[164:167], v[172:175], v[124:127]
	v_mfma_f32_16x16x32_bf16 v[104:107], v[156:159], v[202:205], v[104:107]
	v_mfma_f32_16x16x32_bf16 v[108:111], v[164:167], v[202:205], v[108:111]
	v_mfma_f32_16x16x32_bf16 v[88:91], v[156:159], v[210:213], v[88:91]
	v_mfma_f32_16x16x32_bf16 v[92:95], v[164:167], v[210:213], v[92:95]
	v_mfma_f32_16x16x32_bf16 v[64:67], v[156:159], v[218:221], v[64:67]
	v_mfma_f32_16x16x32_bf16 v[68:71], v[164:167], v[218:221], v[68:71]
	v_mfma_f32_16x16x32_bf16 v[120:123], v[160:163], v[198:201], v[120:123]
	v_mfma_f32_16x16x32_bf16 v[124:127], v[168:171], v[198:201], v[124:127]
	v_mfma_f32_16x16x32_bf16 v[104:107], v[160:163], v[206:209], v[104:107]
	v_mfma_f32_16x16x32_bf16 v[108:111], v[168:171], v[206:209], v[108:111]
	v_mfma_f32_16x16x32_bf16 v[88:91], v[160:163], v[214:217], v[88:91]
	v_mfma_f32_16x16x32_bf16 v[92:95], v[168:171], v[214:217], v[92:95]
	v_mfma_f32_16x16x32_bf16 v[64:67], v[160:163], v[222:225], v[64:67]
	v_mfma_f32_16x16x32_bf16 v[68:71], v[168:171], v[222:225], v[68:71]
	s_barrier
	s_setprio 0
	s_mov_b32 m0, s83
	v_lshl_add_u64 v[176:177], s[50:51], 0, v[128:129]
	ds_read_b128 v[172:175], v139 offset:16384
	ds_read_b128 v[198:201], v139 offset:17408
	ds_read_b128 v[202:205], v139 offset:18432
	ds_read_b128 v[206:209], v139 offset:19456
	ds_read_b128 v[210:213], v139 offset:20480
	ds_read_b128 v[214:217], v139 offset:21504
	ds_read_b128 v[218:221], v139 offset:22528
	ds_read_b128 v[222:225], v139 offset:23552
	global_load_lds_dwordx4 v[176:177], off
	v_lshl_add_u64 v[226:227], s[50:51], 0, v[130:131]
	s_mov_b32 m0, s84
	v_lshl_add_u64 v[228:229], s[60:61], 0, v[128:129]
	global_load_lds_dwordx4 v[226:227], off
	s_mov_b32 m0, s85
	v_lshl_add_u64 v[238:239], s[48:49], 0, v[132:133]
	global_load_lds_dwordx4 v[228:229], off
	v_lshl_add_u64 v[228:229], s[60:61], 0, v[130:131]
	s_mov_b32 m0, s86
	s_nop 0
	global_load_lds_dwordx4 v[228:229], off
	v_lshl_add_u64 v[228:229], s[48:49], 0, v[134:135]
	s_mov_b32 m0, s20
	s_nop 0
	global_load_lds_dwordx4 v[228:229], off
	s_mov_b32 m0, s21
	s_nop 0
	global_load_lds_dwordx4 v[238:239], off
	s_waitcnt vmcnt(8)
	s_waitcnt lgkmcnt(0)
	s_setprio 1
	s_barrier
	v_mfma_f32_16x16x32_bf16 v[56:59], v[140:143], v[172:175], v[56:59]
	v_mfma_f32_16x16x32_bf16 v[60:63], v[148:151], v[172:175], v[60:63]
	v_mfma_f32_16x16x32_bf16 v[32:35], v[140:143], v[202:205], v[32:35]
	v_mfma_f32_16x16x32_bf16 v[36:39], v[148:151], v[202:205], v[36:39]
	v_mfma_f32_16x16x32_bf16 v[16:19], v[140:143], v[210:213], v[16:19]
	v_mfma_f32_16x16x32_bf16 v[20:23], v[148:151], v[210:213], v[20:23]
	v_mfma_f32_16x16x32_bf16 v[0:3], v[140:143], v[218:221], v[0:3]
	v_mfma_f32_16x16x32_bf16 v[4:7], v[148:151], v[218:221], v[4:7]
	v_mfma_f32_16x16x32_bf16 v[56:59], v[144:147], v[198:201], v[56:59]
	v_mfma_f32_16x16x32_bf16 v[60:63], v[152:155], v[198:201], v[60:63]
	v_mfma_f32_16x16x32_bf16 v[32:35], v[144:147], v[206:209], v[32:35]
	v_mfma_f32_16x16x32_bf16 v[36:39], v[152:155], v[206:209], v[36:39]
	v_mfma_f32_16x16x32_bf16 v[16:19], v[144:147], v[214:217], v[16:19]
	v_mfma_f32_16x16x32_bf16 v[20:23], v[152:155], v[214:217], v[20:23]
	v_mfma_f32_16x16x32_bf16 v[0:3], v[144:147], v[222:225], v[0:3]
	v_mfma_f32_16x16x32_bf16 v[4:7], v[152:155], v[222:225], v[4:7]
	v_mfma_f32_16x16x32_bf16 v[76:79], v[156:159], v[172:175], v[76:79]
	v_mfma_f32_16x16x32_bf16 v[84:87], v[164:167], v[172:175], v[84:87]
	v_mfma_f32_16x16x32_bf16 v[44:47], v[156:159], v[202:205], v[44:47]
	v_mfma_f32_16x16x32_bf16 v[52:55], v[164:167], v[202:205], v[52:55]
	v_mfma_f32_16x16x32_bf16 v[24:27], v[156:159], v[210:213], v[24:27]
	v_mfma_f32_16x16x32_bf16 v[28:31], v[164:167], v[210:213], v[28:31]
	v_mfma_f32_16x16x32_bf16 v[8:11], v[156:159], v[218:221], v[8:11]
	v_mfma_f32_16x16x32_bf16 v[12:15], v[164:167], v[218:221], v[12:15]
	v_mfma_f32_16x16x32_bf16 v[76:79], v[160:163], v[198:201], v[76:79]
	v_mfma_f32_16x16x32_bf16 v[84:87], v[168:171], v[198:201], v[84:87]
	v_mfma_f32_16x16x32_bf16 v[44:47], v[160:163], v[206:209], v[44:47]
	v_mfma_f32_16x16x32_bf16 v[52:55], v[168:171], v[206:209], v[52:55]
	v_mfma_f32_16x16x32_bf16 v[24:27], v[160:163], v[214:217], v[24:27]
	v_mfma_f32_16x16x32_bf16 v[28:31], v[168:171], v[214:217], v[28:31]
	v_mfma_f32_16x16x32_bf16 v[8:11], v[160:163], v[222:225], v[8:11]
	v_mfma_f32_16x16x32_bf16 v[12:15], v[168:171], v[222:225], v[12:15]
	s_barrier
	s_setprio 0
	v_add_u32_e32 v152, s87, v137
	v_add_u32_e32 v168, s88, v137
	ds_read_b128 v[140:143], v152
	ds_read_b128 v[144:147], v152 offset:1024
	ds_read_b128 v[148:151], v152 offset:2048
	ds_read_b128 v[152:155], v152 offset:3072
	ds_read_b128 v[156:159], v168
	ds_read_b128 v[160:163], v168 offset:1024
	ds_read_b128 v[164:167], v168 offset:2048
	ds_read_b128 v[168:171], v168 offset:3072
	s_mov_b32 m0, s25
	v_lshl_add_u64 v[240:241], s[46:47], 0, v[134:135]
	ds_read_b128 v[172:175], v139 offset:32768
	ds_read_b128 v[198:201], v139 offset:33792
	ds_read_b128 v[202:205], v139 offset:34816
	ds_read_b128 v[206:209], v139 offset:35840
	ds_read_b128 v[210:213], v139 offset:36864
	ds_read_b128 v[214:217], v139 offset:37888
	ds_read_b128 v[218:221], v139 offset:38912
	ds_read_b128 v[222:225], v139 offset:39936
	global_load_lds_dwordx4 v[240:241], off
	v_lshl_add_u64 v[240:241], s[46:47], 0, v[132:133]
	s_mov_b32 m0, s42
	s_nop 0
	global_load_lds_dwordx4 v[240:241], off
	s_waitcnt vmcnt(8)
	s_waitcnt lgkmcnt(0)
	s_setprio 1
	s_barrier
	v_mfma_f32_16x16x32_bf16 v[112:115], v[140:143], v[172:175], v[112:115]
	v_mfma_f32_16x16x32_bf16 v[116:119], v[148:151], v[172:175], v[116:119]
	v_mfma_f32_16x16x32_bf16 v[96:99], v[140:143], v[202:205], v[96:99]
	v_mfma_f32_16x16x32_bf16 v[100:103], v[148:151], v[202:205], v[100:103]
	v_mfma_f32_16x16x32_bf16 v[72:75], v[140:143], v[210:213], v[72:75]
	v_mfma_f32_16x16x32_bf16 v[80:83], v[148:151], v[210:213], v[80:83]
	v_mfma_f32_16x16x32_bf16 v[40:43], v[140:143], v[218:221], v[40:43]
	v_mfma_f32_16x16x32_bf16 v[48:51], v[148:151], v[218:221], v[48:51]
	v_mfma_f32_16x16x32_bf16 v[112:115], v[144:147], v[198:201], v[112:115]
	v_mfma_f32_16x16x32_bf16 v[116:119], v[152:155], v[198:201], v[116:119]
	v_mfma_f32_16x16x32_bf16 v[96:99], v[144:147], v[206:209], v[96:99]
	v_mfma_f32_16x16x32_bf16 v[100:103], v[152:155], v[206:209], v[100:103]
	v_mfma_f32_16x16x32_bf16 v[72:75], v[144:147], v[214:217], v[72:75]
	v_mfma_f32_16x16x32_bf16 v[80:83], v[152:155], v[214:217], v[80:83]
	v_mfma_f32_16x16x32_bf16 v[40:43], v[144:147], v[222:225], v[40:43]
	v_mfma_f32_16x16x32_bf16 v[48:51], v[152:155], v[222:225], v[48:51]
	v_mfma_f32_16x16x32_bf16 v[120:123], v[156:159], v[172:175], v[120:123]
	v_mfma_f32_16x16x32_bf16 v[124:127], v[164:167], v[172:175], v[124:127]
	v_mfma_f32_16x16x32_bf16 v[104:107], v[156:159], v[202:205], v[104:107]
	v_mfma_f32_16x16x32_bf16 v[108:111], v[164:167], v[202:205], v[108:111]
	v_mfma_f32_16x16x32_bf16 v[88:91], v[156:159], v[210:213], v[88:91]
	v_mfma_f32_16x16x32_bf16 v[92:95], v[164:167], v[210:213], v[92:95]
	v_mfma_f32_16x16x32_bf16 v[64:67], v[156:159], v[218:221], v[64:67]
	v_mfma_f32_16x16x32_bf16 v[68:71], v[164:167], v[218:221], v[68:71]
	v_mfma_f32_16x16x32_bf16 v[120:123], v[160:163], v[198:201], v[120:123]
	v_mfma_f32_16x16x32_bf16 v[124:127], v[168:171], v[198:201], v[124:127]
	v_mfma_f32_16x16x32_bf16 v[104:107], v[160:163], v[206:209], v[104:107]
	v_mfma_f32_16x16x32_bf16 v[108:111], v[168:171], v[206:209], v[108:111]
	v_mfma_f32_16x16x32_bf16 v[88:91], v[160:163], v[214:217], v[88:91]
	v_mfma_f32_16x16x32_bf16 v[92:95], v[168:171], v[214:217], v[92:95]
	v_mfma_f32_16x16x32_bf16 v[64:67], v[160:163], v[222:225], v[64:67]
	v_mfma_f32_16x16x32_bf16 v[68:71], v[168:171], v[222:225], v[68:71]
	s_barrier
	s_setprio 0
	s_mov_b32 m0, s73
	v_lshl_add_u64 v[176:177], v[176:177], 0, s[90:91]
	ds_read_b128 v[172:175], v139 offset:49152
	ds_read_b128 v[198:201], v139 offset:50176
	ds_read_b128 v[202:205], v139 offset:51200
	ds_read_b128 v[206:209], v139 offset:52224
	ds_read_b128 v[210:213], v139 offset:53248
	ds_read_b128 v[214:217], v139 offset:54272
	ds_read_b128 v[218:221], v139 offset:55296
	ds_read_b128 v[222:225], v139 offset:56320
	global_load_lds_dwordx4 v[176:177], off
	v_lshl_add_u64 v[176:177], v[226:227], 0, s[90:91]
	s_mov_b32 m0, s59
	s_nop 0
	global_load_lds_dwordx4 v[176:177], off
	v_lshl_add_u64 v[176:177], s[44:45], 0, v[128:129]
	s_mov_b32 m0, s81
	s_nop 0
	global_load_lds_dwordx4 v[176:177], off
	v_lshl_add_u64 v[176:177], s[44:45], 0, v[130:131]
	s_mov_b32 m0, s74
	s_nop 0
	global_load_lds_dwordx4 v[176:177], off
	v_lshl_add_u64 v[176:177], v[228:229], 0, s[90:91]
	s_mov_b32 m0, s43
	s_nop 0
	global_load_lds_dwordx4 v[176:177], off
	v_lshl_add_u64 v[176:177], v[238:239], 0, s[90:91]
	s_mov_b32 m0, s52
	s_nop 0
	global_load_lds_dwordx4 v[176:177], off
	s_waitcnt vmcnt(8)
	s_waitcnt lgkmcnt(0)
	s_setprio 1
	s_barrier
	v_mfma_f32_16x16x32_bf16 v[56:59], v[140:143], v[172:175], v[56:59]
	v_mfma_f32_16x16x32_bf16 v[60:63], v[148:151], v[172:175], v[60:63]
	v_mfma_f32_16x16x32_bf16 v[32:35], v[140:143], v[202:205], v[32:35]
	v_mfma_f32_16x16x32_bf16 v[36:39], v[148:151], v[202:205], v[36:39]
	v_mfma_f32_16x16x32_bf16 v[16:19], v[140:143], v[210:213], v[16:19]
	v_mfma_f32_16x16x32_bf16 v[20:23], v[148:151], v[210:213], v[20:23]
	v_mfma_f32_16x16x32_bf16 v[0:3], v[140:143], v[218:221], v[0:3]
	v_mfma_f32_16x16x32_bf16 v[4:7], v[148:151], v[218:221], v[4:7]
	v_mfma_f32_16x16x32_bf16 v[56:59], v[144:147], v[198:201], v[56:59]
	v_mfma_f32_16x16x32_bf16 v[60:63], v[152:155], v[198:201], v[60:63]
	v_mfma_f32_16x16x32_bf16 v[32:35], v[144:147], v[206:209], v[32:35]
	v_mfma_f32_16x16x32_bf16 v[36:39], v[152:155], v[206:209], v[36:39]
	v_mfma_f32_16x16x32_bf16 v[16:19], v[144:147], v[214:217], v[16:19]
	v_mfma_f32_16x16x32_bf16 v[20:23], v[152:155], v[214:217], v[20:23]
	v_mfma_f32_16x16x32_bf16 v[0:3], v[144:147], v[222:225], v[0:3]
	v_mfma_f32_16x16x32_bf16 v[4:7], v[152:155], v[222:225], v[4:7]
	v_mfma_f32_16x16x32_bf16 v[76:79], v[156:159], v[172:175], v[76:79]
	v_mfma_f32_16x16x32_bf16 v[84:87], v[164:167], v[172:175], v[84:87]
	v_mfma_f32_16x16x32_bf16 v[44:47], v[156:159], v[202:205], v[44:47]
	v_mfma_f32_16x16x32_bf16 v[52:55], v[164:167], v[202:205], v[52:55]
	v_mfma_f32_16x16x32_bf16 v[24:27], v[156:159], v[210:213], v[24:27]
	v_mfma_f32_16x16x32_bf16 v[28:31], v[164:167], v[210:213], v[28:31]
	v_mfma_f32_16x16x32_bf16 v[8:11], v[156:159], v[218:221], v[8:11]
	v_mfma_f32_16x16x32_bf16 v[12:15], v[164:167], v[218:221], v[12:15]
	v_mfma_f32_16x16x32_bf16 v[76:79], v[160:163], v[198:201], v[76:79]
	v_mfma_f32_16x16x32_bf16 v[84:87], v[168:171], v[198:201], v[84:87]
	v_mfma_f32_16x16x32_bf16 v[44:47], v[160:163], v[206:209], v[44:47]
	v_mfma_f32_16x16x32_bf16 v[52:55], v[168:171], v[206:209], v[52:55]
	v_mfma_f32_16x16x32_bf16 v[24:27], v[160:163], v[214:217], v[24:27]
	v_mfma_f32_16x16x32_bf16 v[28:31], v[168:171], v[214:217], v[28:31]
	v_mfma_f32_16x16x32_bf16 v[8:11], v[160:163], v[222:225], v[8:11]
	v_mfma_f32_16x16x32_bf16 v[12:15], v[168:171], v[222:225], v[12:15]
	s_barrier
	s_setprio 0
	s_movk_i32 s46, 0x100
	s_andn2_b64 vcc, exec, s[38:39]
	s_mov_b64 s[44:45], -1
	s_mov_b64 s[38:39], 0
	s_cbranch_vccz .LBB0_344
	s_and_b64 vcc, exec, s[14:15]
	s_cbranch_vccz .LBB0_347
	s_barrier

.LBB0_360:
	s_add_u32 s39, s18, s38
	s_addc_u32 s48, s19, 0
	s_add_u32 s44, s39, 0x100
	s_addc_u32 s45, s48, 0
	s_and_b64 s[30:31], s[36:37], exec
	s_cselect_b32 s45, s15, s45
	s_cselect_b32 s44, s55, s44
	s_add_u32 s30, s24, s38
	s_addc_u32 s31, s25, 0
	s_add_u32 s38, s30, 0x100
	s_addc_u32 s46, s31, 0
	s_add_i32 s59, 0, 0x10000
	s_and_b64 s[30:31], s[36:37], exec
	s_cselect_b32 s47, s13, s46
	s_cselect_b32 s46, s56, s38
	s_add_i32 s37, 0, 0x14000
	s_add_u32 s30, s39, 0x10080
	s_addc_u32 s31, s48, 0
	s_add_i32 s67, s59, s40
	s_add_i32 m0, s17, 0xc000
	s_add_i32 s61, s17, 0xe000
	s_add_i32 s73, s67, 0x2000
	s_add_u32 s48, s46, 0x10000
	v_add_u32_e32 v152, s59, v137
	v_add_u32_e32 v168, s37, v137
	s_addc_u32 s49, s47, 0
	s_add_i32 s74, s37, s40
	ds_read_b128 v[140:143], v152
	ds_read_b128 v[144:147], v152 offset:1024
	ds_read_b128 v[148:151], v152 offset:2048
	ds_read_b128 v[152:155], v152 offset:3072
	ds_read_b128 v[156:159], v168
	ds_read_b128 v[160:163], v168 offset:1024
	ds_read_b128 v[164:167], v168 offset:2048
	ds_read_b128 v[168:171], v168 offset:3072
	s_add_i32 s81, s74, 0x2000
	s_add_i32 s82, 0, 0x18000
	s_add_i32 s83, 0, 0x1c000
	s_add_u32 s38, s44, 0x10000
	s_addc_u32 s39, s45, 0
	s_add_i32 s58, s82, s40
	s_add_i32 s57, s58, 0x2000
	s_add_u32 s36, s46, 0x10080
	s_addc_u32 s37, s47, 0
	s_add_i32 s60, s83, s40
	s_add_i32 s59, s60, 0x2000
	v_lshl_add_u64 v[176:177], s[30:31], 0, v[134:135]
	ds_read_b128 v[172:175], v139
	ds_read_b128 v[198:201], v139 offset:1024
	ds_read_b128 v[202:205], v139 offset:2048
	ds_read_b128 v[206:209], v139 offset:3072
	ds_read_b128 v[210:213], v139 offset:4096
	ds_read_b128 v[214:217], v139 offset:5120
	ds_read_b128 v[218:221], v139 offset:6144
	ds_read_b128 v[222:225], v139 offset:7168
	global_load_lds_dwordx4 v[176:177], off
	v_lshl_add_u64 v[176:177], s[30:31], 0, v[132:133]
	s_mov_b32 m0, s61
	s_nop 0
	global_load_lds_dwordx4 v[176:177], off
	s_waitcnt vmcnt(8)
	s_waitcnt lgkmcnt(0)
	s_setprio 1
	s_barrier
	v_mfma_f32_16x16x32_bf16 v[108:111], v[140:143], v[172:175], v[108:111]
	v_mfma_f32_16x16x32_bf16 v[116:119], v[148:151], v[172:175], v[116:119]
	v_mfma_f32_16x16x32_bf16 v[92:95], v[140:143], v[202:205], v[92:95]
	v_mfma_f32_16x16x32_bf16 v[100:103], v[148:151], v[202:205], v[100:103]
	v_mfma_f32_16x16x32_bf16 v[68:71], v[140:143], v[210:213], v[68:71]
	v_mfma_f32_16x16x32_bf16 v[76:79], v[148:151], v[210:213], v[76:79]
	v_mfma_f32_16x16x32_bf16 v[40:43], v[140:143], v[218:221], v[40:43]
	v_mfma_f32_16x16x32_bf16 v[44:47], v[148:151], v[218:221], v[44:47]
	v_mfma_f32_16x16x32_bf16 v[108:111], v[144:147], v[198:201], v[108:111]
	v_mfma_f32_16x16x32_bf16 v[116:119], v[152:155], v[198:201], v[116:119]
	v_mfma_f32_16x16x32_bf16 v[92:95], v[144:147], v[206:209], v[92:95]
	v_mfma_f32_16x16x32_bf16 v[100:103], v[152:155], v[206:209], v[100:103]
	v_mfma_f32_16x16x32_bf16 v[68:71], v[144:147], v[214:217], v[68:71]
	v_mfma_f32_16x16x32_bf16 v[76:79], v[152:155], v[214:217], v[76:79]
	v_mfma_f32_16x16x32_bf16 v[40:43], v[144:147], v[222:225], v[40:43]
	v_mfma_f32_16x16x32_bf16 v[44:47], v[152:155], v[222:225], v[44:47]
	v_mfma_f32_16x16x32_bf16 v[120:123], v[156:159], v[172:175], v[120:123]
	v_mfma_f32_16x16x32_bf16 v[124:127], v[164:167], v[172:175], v[124:127]
	v_mfma_f32_16x16x32_bf16 v[104:107], v[156:159], v[202:205], v[104:107]
	v_mfma_f32_16x16x32_bf16 v[112:115], v[164:167], v[202:205], v[112:115]
	v_mfma_f32_16x16x32_bf16 v[88:91], v[156:159], v[210:213], v[88:91]
	v_mfma_f32_16x16x32_bf16 v[96:99], v[164:167], v[210:213], v[96:99]
	v_mfma_f32_16x16x32_bf16 v[64:67], v[156:159], v[218:221], v[64:67]
	v_mfma_f32_16x16x32_bf16 v[72:75], v[164:167], v[218:221], v[72:75]
	v_mfma_f32_16x16x32_bf16 v[120:123], v[160:163], v[198:201], v[120:123]
	v_mfma_f32_16x16x32_bf16 v[124:127], v[168:171], v[198:201], v[124:127]
	v_mfma_f32_16x16x32_bf16 v[104:107], v[160:163], v[206:209], v[104:107]
	v_mfma_f32_16x16x32_bf16 v[112:115], v[168:171], v[206:209], v[112:115]
	v_mfma_f32_16x16x32_bf16 v[88:91], v[160:163], v[214:217], v[88:91]
	v_mfma_f32_16x16x32_bf16 v[96:99], v[168:171], v[214:217], v[96:99]
	v_mfma_f32_16x16x32_bf16 v[64:67], v[160:163], v[222:225], v[64:67]
	v_mfma_f32_16x16x32_bf16 v[72:75], v[168:171], v[222:225], v[72:75]
	s_barrier
	s_setprio 0
	s_mov_b32 m0, s67
	v_lshl_add_u64 v[176:177], s[46:47], 0, v[128:129]
	ds_read_b128 v[172:175], v139 offset:16384
	ds_read_b128 v[198:201], v139 offset:17408
	ds_read_b128 v[202:205], v139 offset:18432
	ds_read_b128 v[206:209], v139 offset:19456
	ds_read_b128 v[210:213], v139 offset:20480
	ds_read_b128 v[214:217], v139 offset:21504
	ds_read_b128 v[218:221], v139 offset:22528
	ds_read_b128 v[222:225], v139 offset:23552
	global_load_lds_dwordx4 v[176:177], off
	v_lshl_add_u64 v[226:227], s[46:47], 0, v[130:131]
	s_mov_b32 m0, s73
	v_lshl_add_u64 v[228:229], s[48:49], 0, v[128:129]
	global_load_lds_dwordx4 v[226:227], off
	s_mov_b32 m0, s74
	v_lshl_add_u64 v[238:239], s[44:45], 0, v[132:133]
	global_load_lds_dwordx4 v[228:229], off
	v_lshl_add_u64 v[228:229], s[48:49], 0, v[130:131]
	s_mov_b32 m0, s81
	s_nop 0
	global_load_lds_dwordx4 v[228:229], off
	v_lshl_add_u64 v[228:229], s[44:45], 0, v[134:135]
	s_mov_b32 m0, s17
	s_nop 0
	global_load_lds_dwordx4 v[228:229], off
	s_mov_b32 m0, s20
	s_nop 0
	global_load_lds_dwordx4 v[238:239], off
	s_waitcnt vmcnt(8)
	s_waitcnt lgkmcnt(0)
	s_setprio 1
	s_barrier
	v_mfma_f32_16x16x32_bf16 v[52:55], v[140:143], v[172:175], v[52:55]
	v_mfma_f32_16x16x32_bf16 v[60:63], v[148:151], v[172:175], v[60:63]
	v_mfma_f32_16x16x32_bf16 v[28:31], v[140:143], v[202:205], v[28:31]
	v_mfma_f32_16x16x32_bf16 v[36:39], v[148:151], v[202:205], v[36:39]
	v_mfma_f32_16x16x32_bf16 v[12:15], v[140:143], v[210:213], v[12:15]
	v_mfma_f32_16x16x32_bf16 v[16:19], v[148:151], v[210:213], v[16:19]
	v_mfma_f32_16x16x32_bf16 v[0:3], v[140:143], v[218:221], v[0:3]
	v_mfma_f32_16x16x32_bf16 v[4:7], v[148:151], v[218:221], v[4:7]
	v_mfma_f32_16x16x32_bf16 v[52:55], v[144:147], v[198:201], v[52:55]
	v_mfma_f32_16x16x32_bf16 v[60:63], v[152:155], v[198:201], v[60:63]
	v_mfma_f32_16x16x32_bf16 v[28:31], v[144:147], v[206:209], v[28:31]
	v_mfma_f32_16x16x32_bf16 v[36:39], v[152:155], v[206:209], v[36:39]
	v_mfma_f32_16x16x32_bf16 v[12:15], v[144:147], v[214:217], v[12:15]
	v_mfma_f32_16x16x32_bf16 v[16:19], v[152:155], v[214:217], v[16:19]
	v_mfma_f32_16x16x32_bf16 v[0:3], v[144:147], v[222:225], v[0:3]
	v_mfma_f32_16x16x32_bf16 v[4:7], v[152:155], v[222:225], v[4:7]
	v_mfma_f32_16x16x32_bf16 v[80:83], v[156:159], v[172:175], v[80:83]
	v_mfma_f32_16x16x32_bf16 v[84:87], v[164:167], v[172:175], v[84:87]
	v_mfma_f32_16x16x32_bf16 v[48:51], v[156:159], v[202:205], v[48:51]
	v_mfma_f32_16x16x32_bf16 v[56:59], v[164:167], v[202:205], v[56:59]
	v_mfma_f32_16x16x32_bf16 v[24:27], v[156:159], v[210:213], v[24:27]
	v_mfma_f32_16x16x32_bf16 v[32:35], v[164:167], v[210:213], v[32:35]
	v_mfma_f32_16x16x32_bf16 v[8:11], v[156:159], v[218:221], v[8:11]
	v_mfma_f32_16x16x32_bf16 v[20:23], v[164:167], v[218:221], v[20:23]
	v_mfma_f32_16x16x32_bf16 v[80:83], v[160:163], v[198:201], v[80:83]
	v_mfma_f32_16x16x32_bf16 v[84:87], v[168:171], v[198:201], v[84:87]
	v_mfma_f32_16x16x32_bf16 v[48:51], v[160:163], v[206:209], v[48:51]
	v_mfma_f32_16x16x32_bf16 v[56:59], v[168:171], v[206:209], v[56:59]
	v_mfma_f32_16x16x32_bf16 v[24:27], v[160:163], v[214:217], v[24:27]
	v_mfma_f32_16x16x32_bf16 v[32:35], v[168:171], v[214:217], v[32:35]
	v_mfma_f32_16x16x32_bf16 v[8:11], v[160:163], v[222:225], v[8:11]
	v_mfma_f32_16x16x32_bf16 v[20:23], v[168:171], v[222:225], v[20:23]
	s_barrier
	s_setprio 0
	v_add_u32_e32 v152, s82, v137
	v_add_u32_e32 v168, s83, v137
	ds_read_b128 v[140:143], v152
	ds_read_b128 v[144:147], v152 offset:1024
	ds_read_b128 v[148:151], v152 offset:2048
	ds_read_b128 v[152:155], v152 offset:3072
	ds_read_b128 v[156:159], v168
	ds_read_b128 v[160:163], v168 offset:1024
	ds_read_b128 v[164:167], v168 offset:2048
	ds_read_b128 v[168:171], v168 offset:3072
	s_mov_b32 m0, s21
	v_lshl_add_u64 v[240:241], s[38:39], 0, v[134:135]
	ds_read_b128 v[172:175], v139 offset:32768
	ds_read_b128 v[198:201], v139 offset:33792
	ds_read_b128 v[202:205], v139 offset:34816
	ds_read_b128 v[206:209], v139 offset:35840
	ds_read_b128 v[210:213], v139 offset:36864
	ds_read_b128 v[214:217], v139 offset:37888
	ds_read_b128 v[218:221], v139 offset:38912
	ds_read_b128 v[222:225], v139 offset:39936
	global_load_lds_dwordx4 v[240:241], off
	v_lshl_add_u64 v[240:241], s[38:39], 0, v[132:133]
	s_mov_b32 m0, s42
	s_nop 0
	global_load_lds_dwordx4 v[240:241], off
	s_waitcnt vmcnt(8)
	s_waitcnt lgkmcnt(0)
	s_setprio 1
	s_barrier
	v_mfma_f32_16x16x32_bf16 v[108:111], v[140:143], v[172:175], v[108:111]
	v_mfma_f32_16x16x32_bf16 v[116:119], v[148:151], v[172:175], v[116:119]
	v_mfma_f32_16x16x32_bf16 v[92:95], v[140:143], v[202:205], v[92:95]
	v_mfma_f32_16x16x32_bf16 v[100:103], v[148:151], v[202:205], v[100:103]
	v_mfma_f32_16x16x32_bf16 v[68:71], v[140:143], v[210:213], v[68:71]
	v_mfma_f32_16x16x32_bf16 v[76:79], v[148:151], v[210:213], v[76:79]
	v_mfma_f32_16x16x32_bf16 v[40:43], v[140:143], v[218:221], v[40:43]
	v_mfma_f32_16x16x32_bf16 v[44:47], v[148:151], v[218:221], v[44:47]
	v_mfma_f32_16x16x32_bf16 v[108:111], v[144:147], v[198:201], v[108:111]
	v_mfma_f32_16x16x32_bf16 v[116:119], v[152:155], v[198:201], v[116:119]
	v_mfma_f32_16x16x32_bf16 v[92:95], v[144:147], v[206:209], v[92:95]
	v_mfma_f32_16x16x32_bf16 v[100:103], v[152:155], v[206:209], v[100:103]
	v_mfma_f32_16x16x32_bf16 v[68:71], v[144:147], v[214:217], v[68:71]
	v_mfma_f32_16x16x32_bf16 v[76:79], v[152:155], v[214:217], v[76:79]
	v_mfma_f32_16x16x32_bf16 v[40:43], v[144:147], v[222:225], v[40:43]
	v_mfma_f32_16x16x32_bf16 v[44:47], v[152:155], v[222:225], v[44:47]
	v_mfma_f32_16x16x32_bf16 v[120:123], v[156:159], v[172:175], v[120:123]
	v_mfma_f32_16x16x32_bf16 v[124:127], v[164:167], v[172:175], v[124:127]
	v_mfma_f32_16x16x32_bf16 v[104:107], v[156:159], v[202:205], v[104:107]
	v_mfma_f32_16x16x32_bf16 v[112:115], v[164:167], v[202:205], v[112:115]
	v_mfma_f32_16x16x32_bf16 v[88:91], v[156:159], v[210:213], v[88:91]
	v_mfma_f32_16x16x32_bf16 v[96:99], v[164:167], v[210:213], v[96:99]
	v_mfma_f32_16x16x32_bf16 v[64:67], v[156:159], v[218:221], v[64:67]
	v_mfma_f32_16x16x32_bf16 v[72:75], v[164:167], v[218:221], v[72:75]
	v_mfma_f32_16x16x32_bf16 v[120:123], v[160:163], v[198:201], v[120:123]
	v_mfma_f32_16x16x32_bf16 v[124:127], v[168:171], v[198:201], v[124:127]
	v_mfma_f32_16x16x32_bf16 v[104:107], v[160:163], v[206:209], v[104:107]
	v_mfma_f32_16x16x32_bf16 v[112:115], v[168:171], v[206:209], v[112:115]
	v_mfma_f32_16x16x32_bf16 v[88:91], v[160:163], v[214:217], v[88:91]
	v_mfma_f32_16x16x32_bf16 v[96:99], v[168:171], v[214:217], v[96:99]
	v_mfma_f32_16x16x32_bf16 v[64:67], v[160:163], v[222:225], v[64:67]
	v_mfma_f32_16x16x32_bf16 v[72:75], v[168:171], v[222:225], v[72:75]
	s_barrier
	s_setprio 0
	s_mov_b32 m0, s58
	v_lshl_add_u64 v[176:177], v[176:177], 0, s[90:91]
	ds_read_b128 v[172:175], v139 offset:49152
	ds_read_b128 v[198:201], v139 offset:50176
	ds_read_b128 v[202:205], v139 offset:51200
	ds_read_b128 v[206:209], v139 offset:52224
	ds_read_b128 v[210:213], v139 offset:53248
	ds_read_b128 v[214:217], v139 offset:54272
	ds_read_b128 v[218:221], v139 offset:55296
	ds_read_b128 v[222:225], v139 offset:56320
	global_load_lds_dwordx4 v[176:177], off
	v_lshl_add_u64 v[176:177], v[226:227], 0, s[90:91]
	s_mov_b32 m0, s57
	s_nop 0
	global_load_lds_dwordx4 v[176:177], off
	v_lshl_add_u64 v[176:177], s[36:37], 0, v[128:129]
	s_mov_b32 m0, s60
	s_nop 0
	global_load_lds_dwordx4 v[176:177], off
	v_lshl_add_u64 v[176:177], s[36:37], 0, v[130:131]
	s_mov_b32 m0, s59
	s_nop 0
	global_load_lds_dwordx4 v[176:177], off
	v_lshl_add_u64 v[176:177], v[228:229], 0, s[90:91]
	s_mov_b32 m0, s43
	s_nop 0
	global_load_lds_dwordx4 v[176:177], off
	v_lshl_add_u64 v[176:177], v[238:239], 0, s[90:91]
	s_mov_b32 m0, s50
	s_nop 0
	global_load_lds_dwordx4 v[176:177], off
	s_waitcnt vmcnt(8)
	s_waitcnt lgkmcnt(0)
	s_setprio 1
	s_barrier
	v_mfma_f32_16x16x32_bf16 v[52:55], v[140:143], v[172:175], v[52:55]
	v_mfma_f32_16x16x32_bf16 v[60:63], v[148:151], v[172:175], v[60:63]
	v_mfma_f32_16x16x32_bf16 v[28:31], v[140:143], v[202:205], v[28:31]
	v_mfma_f32_16x16x32_bf16 v[36:39], v[148:151], v[202:205], v[36:39]
	v_mfma_f32_16x16x32_bf16 v[12:15], v[140:143], v[210:213], v[12:15]
	v_mfma_f32_16x16x32_bf16 v[16:19], v[148:151], v[210:213], v[16:19]
	v_mfma_f32_16x16x32_bf16 v[0:3], v[140:143], v[218:221], v[0:3]
	v_mfma_f32_16x16x32_bf16 v[4:7], v[148:151], v[218:221], v[4:7]
	v_mfma_f32_16x16x32_bf16 v[52:55], v[144:147], v[198:201], v[52:55]
	v_mfma_f32_16x16x32_bf16 v[60:63], v[152:155], v[198:201], v[60:63]
	v_mfma_f32_16x16x32_bf16 v[28:31], v[144:147], v[206:209], v[28:31]
	v_mfma_f32_16x16x32_bf16 v[36:39], v[152:155], v[206:209], v[36:39]
	v_mfma_f32_16x16x32_bf16 v[12:15], v[144:147], v[214:217], v[12:15]
	v_mfma_f32_16x16x32_bf16 v[16:19], v[152:155], v[214:217], v[16:19]
	v_mfma_f32_16x16x32_bf16 v[0:3], v[144:147], v[222:225], v[0:3]
	v_mfma_f32_16x16x32_bf16 v[4:7], v[152:155], v[222:225], v[4:7]
	v_mfma_f32_16x16x32_bf16 v[80:83], v[156:159], v[172:175], v[80:83]
	v_mfma_f32_16x16x32_bf16 v[84:87], v[164:167], v[172:175], v[84:87]
	v_mfma_f32_16x16x32_bf16 v[48:51], v[156:159], v[202:205], v[48:51]
	v_mfma_f32_16x16x32_bf16 v[56:59], v[164:167], v[202:205], v[56:59]
	v_mfma_f32_16x16x32_bf16 v[24:27], v[156:159], v[210:213], v[24:27]
	v_mfma_f32_16x16x32_bf16 v[32:35], v[164:167], v[210:213], v[32:35]
	v_mfma_f32_16x16x32_bf16 v[8:11], v[156:159], v[218:221], v[8:11]
	v_mfma_f32_16x16x32_bf16 v[20:23], v[164:167], v[218:221], v[20:23]
	v_mfma_f32_16x16x32_bf16 v[80:83], v[160:163], v[198:201], v[80:83]
	v_mfma_f32_16x16x32_bf16 v[84:87], v[168:171], v[198:201], v[84:87]
	v_mfma_f32_16x16x32_bf16 v[48:51], v[160:163], v[206:209], v[48:51]
	v_mfma_f32_16x16x32_bf16 v[56:59], v[168:171], v[206:209], v[56:59]
	v_mfma_f32_16x16x32_bf16 v[24:27], v[160:163], v[214:217], v[24:27]
	v_mfma_f32_16x16x32_bf16 v[32:35], v[168:171], v[214:217], v[32:35]
	v_mfma_f32_16x16x32_bf16 v[8:11], v[160:163], v[222:225], v[8:11]
	v_mfma_f32_16x16x32_bf16 v[20:23], v[168:171], v[222:225], v[20:23]
	s_barrier
	s_setprio 0
	s_movk_i32 s38, 0x100
	s_andn2_b64 vcc, exec, s[34:35]
	s_mov_b64 s[36:37], -1
	s_mov_b64 s[34:35], 0
	s_cbranch_vccz .LBB0_360
	s_and_b64 vcc, exec, s[10:11]
	s_cbranch_vccz .LBB0_363
	s_barrier

.LBB0_395:
	s_add_u32 s16, s14, 0xfffc0080
	s_addc_u32 s17, s15, -1
	s_add_i32 s30, 0, 0x10000
	s_cmp_eq_u32 s48, 12
	s_cselect_b32 s27, s21, s17
	s_cselect_b32 s26, s44, s16
	v_add_u32_e32 v142, s30, v145
	s_cselect_b32 s17, s19, s47
	s_cselect_b32 s16, s45, s46
	s_add_i32 s49, 0, 0x14000
	ds_read_b128 v[146:149], v142
	ds_read_b128 v[150:153], v142 offset:1024
	ds_read_b128 v[154:157], v142 offset:2048
	ds_read_b128 v[158:161], v142 offset:3072
	v_add_u32_e32 v142, s49, v145
	ds_read_b128 v[162:165], v142
	ds_read_b128 v[166:169], v142 offset:1024
	ds_read_b128 v[170:173], v142 offset:2048
	ds_read_b128 v[174:177], v142 offset:3072
	v_lshl_add_u64 v[142:143], s[14:15], 0, v[138:139]
	s_add_i32 m0, s9, 0xc000
	ds_read_b128 v[198:201], v141
	ds_read_b128 v[202:205], v141 offset:1024
	ds_read_b128 v[206:209], v141 offset:2048
	ds_read_b128 v[210:213], v141 offset:3072
	ds_read_b128 v[214:217], v141 offset:4096
	ds_read_b128 v[218:221], v141 offset:5120
	ds_read_b128 v[222:225], v141 offset:6144
	ds_read_b128 v[226:229], v141 offset:7168
	global_load_lds_dwordx4 v[142:143], off
	v_lshl_add_u64 v[142:143], s[14:15], 0, v[136:137]
	s_add_i32 m0, s9, 0xe000
	s_nop 0
	global_load_lds_dwordx4 v[142:143], off
	s_waitcnt vmcnt(8)
	s_waitcnt lgkmcnt(0)
	s_setprio 1
	s_barrier
	v_mfma_f32_16x16x32_bf16 v[20:23], v[146:149], v[198:201], v[20:23]
	v_mfma_f32_16x16x32_bf16 v[28:31], v[154:157], v[198:201], v[28:31]
	v_mfma_f32_16x16x32_bf16 v[12:15], v[146:149], v[206:209], v[12:15]
	v_mfma_f32_16x16x32_bf16 v[24:27], v[154:157], v[206:209], v[24:27]
	v_mfma_f32_16x16x32_bf16 v[4:7], v[146:149], v[214:217], v[4:7]
	v_mfma_f32_16x16x32_bf16 v[16:19], v[154:157], v[214:217], v[16:19]
	v_mfma_f32_16x16x32_bf16 v[0:3], v[146:149], v[222:225], v[0:3]
	v_mfma_f32_16x16x32_bf16 v[8:11], v[154:157], v[222:225], v[8:11]
	v_mfma_f32_16x16x32_bf16 v[20:23], v[150:153], v[202:205], v[20:23]
	v_mfma_f32_16x16x32_bf16 v[28:31], v[158:161], v[202:205], v[28:31]
	v_mfma_f32_16x16x32_bf16 v[12:15], v[150:153], v[210:213], v[12:15]
	v_mfma_f32_16x16x32_bf16 v[24:27], v[158:161], v[210:213], v[24:27]
	v_mfma_f32_16x16x32_bf16 v[4:7], v[150:153], v[218:221], v[4:7]
	v_mfma_f32_16x16x32_bf16 v[16:19], v[158:161], v[218:221], v[16:19]
	v_mfma_f32_16x16x32_bf16 v[0:3], v[150:153], v[226:229], v[0:3]
	v_mfma_f32_16x16x32_bf16 v[8:11], v[158:161], v[226:229], v[8:11]
	v_mfma_f32_16x16x32_bf16 v[84:87], v[162:165], v[198:201], v[84:87]
	v_mfma_f32_16x16x32_bf16 v[92:95], v[170:173], v[198:201], v[92:95]
	v_mfma_f32_16x16x32_bf16 v[72:75], v[162:165], v[206:209], v[72:75]
	v_mfma_f32_16x16x32_bf16 v[88:91], v[170:173], v[206:209], v[88:91]
	v_mfma_f32_16x16x32_bf16 v[60:63], v[162:165], v[214:217], v[60:63]
	v_mfma_f32_16x16x32_bf16 v[80:83], v[170:173], v[214:217], v[80:83]
	v_mfma_f32_16x16x32_bf16 v[48:51], v[162:165], v[222:225], v[48:51]
	v_mfma_f32_16x16x32_bf16 v[68:71], v[170:173], v[222:225], v[68:71]
	v_mfma_f32_16x16x32_bf16 v[84:87], v[166:169], v[202:205], v[84:87]
	v_mfma_f32_16x16x32_bf16 v[92:95], v[174:177], v[202:205], v[92:95]
	v_mfma_f32_16x16x32_bf16 v[72:75], v[166:169], v[210:213], v[72:75]
	v_mfma_f32_16x16x32_bf16 v[88:91], v[174:177], v[210:213], v[88:91]
	v_mfma_f32_16x16x32_bf16 v[60:63], v[166:169], v[218:221], v[60:63]
	v_mfma_f32_16x16x32_bf16 v[80:83], v[174:177], v[218:221], v[80:83]
	v_mfma_f32_16x16x32_bf16 v[48:51], v[166:169], v[226:229], v[48:51]
	v_mfma_f32_16x16x32_bf16 v[68:71], v[174:177], v[226:229], v[68:71]
	s_barrier
	s_setprio 0
	s_add_i32 s30, s30, s34
	v_lshl_add_u64 v[142:143], s[16:17], 0, v[128:129]
	s_mov_b32 m0, s30
	ds_read_b128 v[198:201], v141 offset:16384
	ds_read_b128 v[202:205], v141 offset:17408
	ds_read_b128 v[206:209], v141 offset:18432
	ds_read_b128 v[210:213], v141 offset:19456
	ds_read_b128 v[214:217], v141 offset:20480
	ds_read_b128 v[218:221], v141 offset:21504
	ds_read_b128 v[222:225], v141 offset:22528
	ds_read_b128 v[226:229], v141 offset:23552
	global_load_lds_dwordx4 v[142:143], off
	s_add_i32 m0, s30, 0x2000
	s_add_u32 s30, s16, 0x40000
	v_lshl_add_u64 v[238:239], s[16:17], 0, v[130:131]
	s_addc_u32 s31, s17, 0
	s_add_i32 s49, s49, s34
	global_load_lds_dwordx4 v[238:239], off
	v_lshl_add_u64 v[240:241], s[30:31], 0, v[128:129]
	s_mov_b32 m0, s49
	v_lshl_add_u64 v[242:243], s[26:27], 0, v[132:133]
	global_load_lds_dwordx4 v[240:241], off
	v_lshl_add_u64 v[240:241], s[30:31], 0, v[130:131]
	s_add_i32 m0, s49, 0x2000
	s_nop 0
	global_load_lds_dwordx4 v[240:241], off
	v_lshl_add_u64 v[240:241], s[26:27], 0, v[134:135]
	s_mov_b32 m0, s9
	s_nop 0
	global_load_lds_dwordx4 v[240:241], off
	s_mov_b32 m0, s36
	s_nop 0
	global_load_lds_dwordx4 v[242:243], off
	s_waitcnt vmcnt(8)
	s_waitcnt lgkmcnt(0)
	s_setprio 1
	s_barrier
	v_mfma_f32_16x16x32_bf16 v[56:59], v[146:149], v[198:201], v[56:59]
	v_mfma_f32_16x16x32_bf16 v[76:79], v[154:157], v[198:201], v[76:79]
	v_mfma_f32_16x16x32_bf16 v[44:47], v[146:149], v[206:209], v[44:47]
	v_mfma_f32_16x16x32_bf16 v[64:67], v[154:157], v[206:209], v[64:67]
	v_mfma_f32_16x16x32_bf16 v[36:39], v[146:149], v[214:217], v[36:39]
	v_mfma_f32_16x16x32_bf16 v[52:55], v[154:157], v[214:217], v[52:55]
	v_mfma_f32_16x16x32_bf16 v[32:35], v[146:149], v[222:225], v[32:35]
	v_mfma_f32_16x16x32_bf16 v[40:43], v[154:157], v[222:225], v[40:43]
	v_mfma_f32_16x16x32_bf16 v[56:59], v[150:153], v[202:205], v[56:59]
	v_mfma_f32_16x16x32_bf16 v[76:79], v[158:161], v[202:205], v[76:79]
	v_mfma_f32_16x16x32_bf16 v[44:47], v[150:153], v[210:213], v[44:47]
	v_mfma_f32_16x16x32_bf16 v[64:67], v[158:161], v[210:213], v[64:67]
	v_mfma_f32_16x16x32_bf16 v[36:39], v[150:153], v[218:221], v[36:39]
	v_mfma_f32_16x16x32_bf16 v[52:55], v[158:161], v[218:221], v[52:55]
	v_mfma_f32_16x16x32_bf16 v[32:35], v[150:153], v[226:229], v[32:35]
	v_mfma_f32_16x16x32_bf16 v[40:43], v[158:161], v[226:229], v[40:43]
	v_mfma_f32_16x16x32_bf16 v[112:115], v[162:165], v[198:201], v[112:115]
	v_mfma_f32_16x16x32_bf16 v[120:123], v[170:173], v[198:201], v[120:123]
	v_mfma_f32_16x16x32_bf16 v[104:107], v[162:165], v[206:209], v[104:107]
	v_mfma_f32_16x16x32_bf16 v[116:119], v[170:173], v[206:209], v[116:119]
	v_mfma_f32_16x16x32_bf16 v[100:103], v[162:165], v[214:217], v[100:103]
	v_mfma_f32_16x16x32_bf16 v[108:111], v[170:173], v[214:217], v[108:111]
	v_mfma_f32_16x16x32_bf16 v[96:99], v[162:165], v[222:225], v[96:99]
	v_mfma_f32_16x16x32_bf16 v[124:127], v[170:173], v[222:225], v[124:127]
	v_mfma_f32_16x16x32_bf16 v[112:115], v[166:169], v[202:205], v[112:115]
	v_mfma_f32_16x16x32_bf16 v[120:123], v[174:177], v[202:205], v[120:123]
	v_mfma_f32_16x16x32_bf16 v[104:107], v[166:169], v[210:213], v[104:107]
	v_mfma_f32_16x16x32_bf16 v[116:119], v[174:177], v[210:213], v[116:119]
	v_mfma_f32_16x16x32_bf16 v[100:103], v[166:169], v[218:221], v[100:103]
	v_mfma_f32_16x16x32_bf16 v[108:111], v[174:177], v[218:221], v[108:111]
	v_mfma_f32_16x16x32_bf16 v[96:99], v[166:169], v[226:229], v[96:99]
	v_mfma_f32_16x16x32_bf16 v[124:127], v[174:177], v[226:229], v[124:127]
	s_barrier
	s_setprio 0
	s_add_i32 s30, 0, 0x18000
	s_add_i32 s31, 0, 0x1c000
	v_add_u32_e32 v158, s30, v145
	v_add_u32_e32 v174, s31, v145
	ds_read_b128 v[146:149], v158
	ds_read_b128 v[150:153], v158 offset:1024
	ds_read_b128 v[154:157], v158 offset:2048
	ds_read_b128 v[158:161], v158 offset:3072
	ds_read_b128 v[162:165], v174
	ds_read_b128 v[166:169], v174 offset:1024
	ds_read_b128 v[170:173], v174 offset:2048
	ds_read_b128 v[174:177], v174 offset:3072
	s_add_u32 s26, s26, 0x40000
	s_addc_u32 s27, s27, 0
	s_mov_b32 m0, s37
	v_lshl_add_u64 v[244:245], s[26:27], 0, v[134:135]
	ds_read_b128 v[198:201], v141 offset:32768
	ds_read_b128 v[202:205], v141 offset:33792
	ds_read_b128 v[206:209], v141 offset:34816
	ds_read_b128 v[210:213], v141 offset:35840
	ds_read_b128 v[214:217], v141 offset:36864
	ds_read_b128 v[218:221], v141 offset:37888
	ds_read_b128 v[222:225], v141 offset:38912
	ds_read_b128 v[226:229], v141 offset:39936
	global_load_lds_dwordx4 v[244:245], off
	v_lshl_add_u64 v[244:245], s[26:27], 0, v[132:133]
	s_mov_b32 m0, s38
	s_nop 0
	global_load_lds_dwordx4 v[244:245], off
	s_waitcnt vmcnt(8)
	s_waitcnt lgkmcnt(0)
	s_setprio 1
	s_barrier
	v_mfma_f32_16x16x32_bf16 v[20:23], v[146:149], v[198:201], v[20:23]
	v_mfma_f32_16x16x32_bf16 v[28:31], v[154:157], v[198:201], v[28:31]
	v_mfma_f32_16x16x32_bf16 v[12:15], v[146:149], v[206:209], v[12:15]
	v_mfma_f32_16x16x32_bf16 v[24:27], v[154:157], v[206:209], v[24:27]
	v_mfma_f32_16x16x32_bf16 v[4:7], v[146:149], v[214:217], v[4:7]
	v_mfma_f32_16x16x32_bf16 v[16:19], v[154:157], v[214:217], v[16:19]
	v_mfma_f32_16x16x32_bf16 v[0:3], v[146:149], v[222:225], v[0:3]
	v_mfma_f32_16x16x32_bf16 v[8:11], v[154:157], v[222:225], v[8:11]
	v_mfma_f32_16x16x32_bf16 v[20:23], v[150:153], v[202:205], v[20:23]
	v_mfma_f32_16x16x32_bf16 v[28:31], v[158:161], v[202:205], v[28:31]
	v_mfma_f32_16x16x32_bf16 v[12:15], v[150:153], v[210:213], v[12:15]
	v_mfma_f32_16x16x32_bf16 v[24:27], v[158:161], v[210:213], v[24:27]
	v_mfma_f32_16x16x32_bf16 v[4:7], v[150:153], v[218:221], v[4:7]
	v_mfma_f32_16x16x32_bf16 v[16:19], v[158:161], v[218:221], v[16:19]
	v_mfma_f32_16x16x32_bf16 v[0:3], v[150:153], v[226:229], v[0:3]
	v_mfma_f32_16x16x32_bf16 v[8:11], v[158:161], v[226:229], v[8:11]
	v_mfma_f32_16x16x32_bf16 v[84:87], v[162:165], v[198:201], v[84:87]
	v_mfma_f32_16x16x32_bf16 v[92:95], v[170:173], v[198:201], v[92:95]
	v_mfma_f32_16x16x32_bf16 v[72:75], v[162:165], v[206:209], v[72:75]
	v_mfma_f32_16x16x32_bf16 v[88:91], v[170:173], v[206:209], v[88:91]
	v_mfma_f32_16x16x32_bf16 v[60:63], v[162:165], v[214:217], v[60:63]
	v_mfma_f32_16x16x32_bf16 v[80:83], v[170:173], v[214:217], v[80:83]
	v_mfma_f32_16x16x32_bf16 v[48:51], v[162:165], v[222:225], v[48:51]
	v_mfma_f32_16x16x32_bf16 v[68:71], v[170:173], v[222:225], v[68:71]
	v_mfma_f32_16x16x32_bf16 v[84:87], v[166:169], v[202:205], v[84:87]
	v_mfma_f32_16x16x32_bf16 v[92:95], v[174:177], v[202:205], v[92:95]
	v_mfma_f32_16x16x32_bf16 v[72:75], v[166:169], v[210:213], v[72:75]
	v_mfma_f32_16x16x32_bf16 v[88:91], v[174:177], v[210:213], v[88:91]
	v_mfma_f32_16x16x32_bf16 v[60:63], v[166:169], v[218:221], v[60:63]
	v_mfma_f32_16x16x32_bf16 v[80:83], v[174:177], v[218:221], v[80:83]
	v_mfma_f32_16x16x32_bf16 v[48:51], v[166:169], v[226:229], v[48:51]
	v_mfma_f32_16x16x32_bf16 v[68:71], v[174:177], v[226:229], v[68:71]
	s_barrier
	s_setprio 0
	s_add_i32 s26, s30, s34
	v_lshl_add_u64 v[142:143], v[142:143], 0, s[90:91]
	s_mov_b32 m0, s26
	ds_read_b128 v[198:201], v141 offset:49152
	ds_read_b128 v[202:205], v141 offset:50176
	ds_read_b128 v[206:209], v141 offset:51200
	ds_read_b128 v[210:213], v141 offset:52224
	ds_read_b128 v[214:217], v141 offset:53248
	ds_read_b128 v[218:221], v141 offset:54272
	ds_read_b128 v[222:225], v141 offset:55296
	ds_read_b128 v[226:229], v141 offset:56320
	global_load_lds_dwordx4 v[142:143], off
	s_add_i32 m0, s26, 0x2000
	s_add_u32 s16, s16, 0x40080
	v_lshl_add_u64 v[142:143], v[238:239], 0, s[90:91]
	s_addc_u32 s17, s17, 0
	s_add_i32 s26, s31, s34
	global_load_lds_dwordx4 v[142:143], off
	v_lshl_add_u64 v[142:143], s[16:17], 0, v[128:129]
	s_mov_b32 m0, s26
	s_nop 0
	global_load_lds_dwordx4 v[142:143], off
	v_lshl_add_u64 v[142:143], s[16:17], 0, v[130:131]
	s_add_i32 m0, s26, 0x2000
	s_nop 0
	global_load_lds_dwordx4 v[142:143], off
	v_lshl_add_u64 v[142:143], v[240:241], 0, s[90:91]
	s_mov_b32 m0, s40
	s_nop 0
	global_load_lds_dwordx4 v[142:143], off
	v_lshl_add_u64 v[142:143], v[242:243], 0, s[90:91]
	s_mov_b32 m0, s41
	s_nop 0
	global_load_lds_dwordx4 v[142:143], off
	s_waitcnt vmcnt(8)
	s_waitcnt lgkmcnt(0)
	s_setprio 1
	s_barrier
	v_mfma_f32_16x16x32_bf16 v[56:59], v[146:149], v[198:201], v[56:59]
	v_mfma_f32_16x16x32_bf16 v[76:79], v[154:157], v[198:201], v[76:79]
	v_mfma_f32_16x16x32_bf16 v[44:47], v[146:149], v[206:209], v[44:47]
	v_mfma_f32_16x16x32_bf16 v[64:67], v[154:157], v[206:209], v[64:67]
	v_mfma_f32_16x16x32_bf16 v[36:39], v[146:149], v[214:217], v[36:39]
	v_mfma_f32_16x16x32_bf16 v[52:55], v[154:157], v[214:217], v[52:55]
	v_mfma_f32_16x16x32_bf16 v[32:35], v[146:149], v[222:225], v[32:35]
	v_mfma_f32_16x16x32_bf16 v[40:43], v[154:157], v[222:225], v[40:43]
	v_mfma_f32_16x16x32_bf16 v[56:59], v[150:153], v[202:205], v[56:59]
	v_mfma_f32_16x16x32_bf16 v[76:79], v[158:161], v[202:205], v[76:79]
	v_mfma_f32_16x16x32_bf16 v[44:47], v[150:153], v[210:213], v[44:47]
	v_mfma_f32_16x16x32_bf16 v[64:67], v[158:161], v[210:213], v[64:67]
	v_mfma_f32_16x16x32_bf16 v[36:39], v[150:153], v[218:221], v[36:39]
	v_mfma_f32_16x16x32_bf16 v[52:55], v[158:161], v[218:221], v[52:55]
	v_mfma_f32_16x16x32_bf16 v[32:35], v[150:153], v[226:229], v[32:35]
	v_mfma_f32_16x16x32_bf16 v[40:43], v[158:161], v[226:229], v[40:43]
	v_mfma_f32_16x16x32_bf16 v[112:115], v[162:165], v[198:201], v[112:115]
	v_mfma_f32_16x16x32_bf16 v[120:123], v[170:173], v[198:201], v[120:123]
	v_mfma_f32_16x16x32_bf16 v[104:107], v[162:165], v[206:209], v[104:107]
	v_mfma_f32_16x16x32_bf16 v[116:119], v[170:173], v[206:209], v[116:119]
	v_mfma_f32_16x16x32_bf16 v[100:103], v[162:165], v[214:217], v[100:103]
	v_mfma_f32_16x16x32_bf16 v[108:111], v[170:173], v[214:217], v[108:111]
	v_mfma_f32_16x16x32_bf16 v[96:99], v[162:165], v[222:225], v[96:99]
	v_mfma_f32_16x16x32_bf16 v[124:127], v[170:173], v[222:225], v[124:127]
	v_mfma_f32_16x16x32_bf16 v[112:115], v[166:169], v[202:205], v[112:115]
	v_mfma_f32_16x16x32_bf16 v[120:123], v[174:177], v[202:205], v[120:123]
	v_mfma_f32_16x16x32_bf16 v[104:107], v[166:169], v[210:213], v[104:107]
	v_mfma_f32_16x16x32_bf16 v[116:119], v[174:177], v[210:213], v[116:119]
	v_mfma_f32_16x16x32_bf16 v[100:103], v[166:169], v[218:221], v[100:103]
	v_mfma_f32_16x16x32_bf16 v[108:111], v[174:177], v[218:221], v[108:111]
	v_mfma_f32_16x16x32_bf16 v[96:99], v[166:169], v[226:229], v[96:99]
	v_mfma_f32_16x16x32_bf16 v[124:127], v[174:177], v[226:229], v[124:127]
	s_barrier
	s_setprio 0
	s_add_i32 s48, s48, 2
	s_add_u32 s46, s46, 0x100
	s_addc_u32 s47, s47, 0
	s_add_u32 s14, s14, 0x100
	s_addc_u32 s15, s15, 0
	s_cmp_gt_u32 s48, 13
	s_cbranch_scc0 .LBB0_395
	s_and_b64 vcc, exec, s[12:13]
	s_cbranch_vccz .LBB0_398
	s_barrier

.LBB0_451:
	s_add_i32 s60, s50, 2
	s_add_u32 s30, s8, 0x80
	s_addc_u32 s31, s9, 0
	s_add_i32 s61, 0, 0x10000
	s_cmp_eq_u32 s21, s50
	s_cselect_b32 s51, s47, s31
	s_cselect_b32 s50, s46, s30
	v_add_u32_e32 v128, s61, v173
	s_cselect_b32 s31, s49, vcc_lo
	s_cselect_b32 s30, s48, s45
	s_add_i32 vcc_hi, 0, 0x14000
	ds_read_b128 v[130:133], v128
	ds_read_b128 v[134:137], v128 offset:1024
	ds_read_b128 v[138:141], v128 offset:2048
	ds_read_b128 v[142:145], v128 offset:3072
	v_add_u32_e32 v128, vcc_hi, v173
	ds_read_b128 v[158:161], v128
	ds_read_b128 v[162:165], v128 offset:1024
	ds_read_b128 v[166:169], v128 offset:2048
	ds_read_b128 v[198:201], v128 offset:3072
	v_lshl_add_u64 v[170:171], s[8:9], 0, v[156:157]
	s_add_i32 m0, s85, 0xc000
	ds_read_b128 v[202:205], v190
	ds_read_b128 v[206:209], v190 offset:1024
	ds_read_b128 v[210:213], v190 offset:2048
	ds_read_b128 v[214:217], v190 offset:3072
	ds_read_b128 v[218:221], v190 offset:4096
	ds_read_b128 v[222:225], v190 offset:5120
	ds_read_b128 v[226:229], v190 offset:6144
	ds_read_b128 v[238:241], v190 offset:7168
	global_load_lds_dwordx4 v[170:171], off
	v_lshl_add_u64 v[170:171], s[8:9], 0, v[154:155]
	s_add_i32 m0, s85, 0xe000
	s_nop 0
	global_load_lds_dwordx4 v[170:171], off
	s_waitcnt vmcnt(8)
	s_waitcnt lgkmcnt(0)
	s_setprio 1
	s_barrier
	v_mfma_f32_16x16x32_bf16 v[124:127], v[130:133], v[202:205], v[124:127]
	v_mfma_f32_16x16x32_bf16 v[120:123], v[138:141], v[202:205], v[120:123]
	v_mfma_f32_16x16x32_bf16 v[108:111], v[130:133], v[210:213], v[108:111]
	v_mfma_f32_16x16x32_bf16 v[104:107], v[138:141], v[210:213], v[104:107]
	v_mfma_f32_16x16x32_bf16 v[92:95], v[130:133], v[218:221], v[92:95]
	v_mfma_f32_16x16x32_bf16 v[88:91], v[138:141], v[218:221], v[88:91]
	v_mfma_f32_16x16x32_bf16 v[76:79], v[130:133], v[226:229], v[76:79]
	v_mfma_f32_16x16x32_bf16 v[72:75], v[138:141], v[226:229], v[72:75]
	v_mfma_f32_16x16x32_bf16 v[124:127], v[134:137], v[206:209], v[124:127]
	v_mfma_f32_16x16x32_bf16 v[120:123], v[142:145], v[206:209], v[120:123]
	v_mfma_f32_16x16x32_bf16 v[108:111], v[134:137], v[214:217], v[108:111]
	v_mfma_f32_16x16x32_bf16 v[104:107], v[142:145], v[214:217], v[104:107]
	v_mfma_f32_16x16x32_bf16 v[92:95], v[134:137], v[222:225], v[92:95]
	v_mfma_f32_16x16x32_bf16 v[88:91], v[142:145], v[222:225], v[88:91]
	v_mfma_f32_16x16x32_bf16 v[76:79], v[134:137], v[238:241], v[76:79]
	v_mfma_f32_16x16x32_bf16 v[72:75], v[142:145], v[238:241], v[72:75]
	v_mfma_f32_16x16x32_bf16 v[116:119], v[158:161], v[202:205], v[116:119]
	v_mfma_f32_16x16x32_bf16 v[112:115], v[166:169], v[202:205], v[112:115]
	v_mfma_f32_16x16x32_bf16 v[100:103], v[158:161], v[210:213], v[100:103]
	v_mfma_f32_16x16x32_bf16 v[96:99], v[166:169], v[210:213], v[96:99]
	v_mfma_f32_16x16x32_bf16 v[84:87], v[158:161], v[218:221], v[84:87]
	v_mfma_f32_16x16x32_bf16 v[80:83], v[166:169], v[218:221], v[80:83]
	v_mfma_f32_16x16x32_bf16 v[68:71], v[158:161], v[226:229], v[68:71]
	v_mfma_f32_16x16x32_bf16 v[64:67], v[166:169], v[226:229], v[64:67]
	v_mfma_f32_16x16x32_bf16 v[116:119], v[162:165], v[206:209], v[116:119]
	v_mfma_f32_16x16x32_bf16 v[112:115], v[198:201], v[206:209], v[112:115]
	v_mfma_f32_16x16x32_bf16 v[100:103], v[162:165], v[214:217], v[100:103]
	v_mfma_f32_16x16x32_bf16 v[96:99], v[198:201], v[214:217], v[96:99]
	v_mfma_f32_16x16x32_bf16 v[84:87], v[162:165], v[222:225], v[84:87]
	v_mfma_f32_16x16x32_bf16 v[80:83], v[198:201], v[222:225], v[80:83]
	v_mfma_f32_16x16x32_bf16 v[68:71], v[162:165], v[238:241], v[68:71]
	v_mfma_f32_16x16x32_bf16 v[64:67], v[198:201], v[238:241], v[64:67]
	s_barrier
	s_setprio 0
	s_add_i32 s61, s61, s82
	v_lshl_add_u64 v[170:171], s[30:31], 0, v[148:149]
	s_mov_b32 m0, s61
	ds_read_b128 v[202:205], v190 offset:16384
	ds_read_b128 v[206:209], v190 offset:17408
	ds_read_b128 v[210:213], v190 offset:18432
	ds_read_b128 v[214:217], v190 offset:19456
	ds_read_b128 v[218:221], v190 offset:20480
	ds_read_b128 v[222:225], v190 offset:21504
	ds_read_b128 v[226:229], v190 offset:22528
	ds_read_b128 v[238:241], v190 offset:23552
	global_load_lds_dwordx4 v[170:171], off
	s_add_i32 m0, s61, 0x2000
	v_lshl_add_u64 v[242:243], s[30:31], 0, v[152:153]
	s_add_u32 s30, s30, s96
	s_addc_u32 s31, s31, 0
	s_add_i32 s61, vcc_hi, s82
	global_load_lds_dwordx4 v[242:243], off
	v_lshl_add_u64 v[244:245], s[30:31], 0, v[148:149]
	s_mov_b32 m0, s61
	v_lshl_add_u64 v[246:247], s[30:31], 0, v[152:153]
	global_load_lds_dwordx4 v[244:245], off
	s_add_i32 m0, s61, 0x2000
	v_lshl_add_u64 v[248:249], s[50:51], 0, v[146:147]
	global_load_lds_dwordx4 v[246:247], off
	s_mov_b32 m0, s85
	v_lshl_add_u64 v[250:251], s[50:51], 0, v[150:151]
	global_load_lds_dwordx4 v[248:249], off
	s_mov_b32 m0, s86
	s_nop 0
	global_load_lds_dwordx4 v[250:251], off
	s_waitcnt vmcnt(8)
	s_waitcnt lgkmcnt(0)
	s_setprio 1
	s_barrier
	v_mfma_f32_16x16x32_bf16 v[60:63], v[130:133], v[202:205], v[60:63]
	v_mfma_f32_16x16x32_bf16 v[56:59], v[138:141], v[202:205], v[56:59]
	v_mfma_f32_16x16x32_bf16 v[44:47], v[130:133], v[210:213], v[44:47]
	v_mfma_f32_16x16x32_bf16 v[40:43], v[138:141], v[210:213], v[40:43]
	v_mfma_f32_16x16x32_bf16 v[28:31], v[130:133], v[218:221], v[28:31]
	v_mfma_f32_16x16x32_bf16 v[24:27], v[138:141], v[218:221], v[24:27]
	v_mfma_f32_16x16x32_bf16 v[12:15], v[130:133], v[226:229], v[12:15]
	v_mfma_f32_16x16x32_bf16 v[8:11], v[138:141], v[226:229], v[8:11]
	v_mfma_f32_16x16x32_bf16 v[60:63], v[134:137], v[206:209], v[60:63]
	v_mfma_f32_16x16x32_bf16 v[56:59], v[142:145], v[206:209], v[56:59]
	v_mfma_f32_16x16x32_bf16 v[44:47], v[134:137], v[214:217], v[44:47]
	v_mfma_f32_16x16x32_bf16 v[40:43], v[142:145], v[214:217], v[40:43]
	v_mfma_f32_16x16x32_bf16 v[28:31], v[134:137], v[222:225], v[28:31]
	v_mfma_f32_16x16x32_bf16 v[24:27], v[142:145], v[222:225], v[24:27]
	v_mfma_f32_16x16x32_bf16 v[12:15], v[134:137], v[238:241], v[12:15]
	v_mfma_f32_16x16x32_bf16 v[8:11], v[142:145], v[238:241], v[8:11]
	v_mfma_f32_16x16x32_bf16 v[52:55], v[158:161], v[202:205], v[52:55]
	v_mfma_f32_16x16x32_bf16 v[48:51], v[166:169], v[202:205], v[48:51]
	v_mfma_f32_16x16x32_bf16 v[36:39], v[158:161], v[210:213], v[36:39]
	v_mfma_f32_16x16x32_bf16 v[32:35], v[166:169], v[210:213], v[32:35]
	v_mfma_f32_16x16x32_bf16 v[20:23], v[158:161], v[218:221], v[20:23]
	v_mfma_f32_16x16x32_bf16 v[16:19], v[166:169], v[218:221], v[16:19]
	v_mfma_f32_16x16x32_bf16 v[4:7], v[158:161], v[226:229], v[4:7]
	v_mfma_f32_16x16x32_bf16 v[0:3], v[166:169], v[226:229], v[0:3]
	v_mfma_f32_16x16x32_bf16 v[52:55], v[162:165], v[206:209], v[52:55]
	v_mfma_f32_16x16x32_bf16 v[48:51], v[198:201], v[206:209], v[48:51]
	v_mfma_f32_16x16x32_bf16 v[36:39], v[162:165], v[214:217], v[36:39]
	v_mfma_f32_16x16x32_bf16 v[32:35], v[198:201], v[214:217], v[32:35]
	v_mfma_f32_16x16x32_bf16 v[20:23], v[162:165], v[222:225], v[20:23]
	v_mfma_f32_16x16x32_bf16 v[16:19], v[198:201], v[222:225], v[16:19]
	v_mfma_f32_16x16x32_bf16 v[4:7], v[162:165], v[238:241], v[4:7]
	v_mfma_f32_16x16x32_bf16 v[0:3], v[198:201], v[238:241], v[0:3]
	s_barrier
	s_setprio 0
	s_add_i32 s61, 0, 0x18000
	v_add_u32_e32 v128, s61, v173
	s_add_i32 vcc_hi, 0, 0x1c000
	ds_read_b128 v[130:133], v128
	ds_read_b128 v[134:137], v128 offset:1024
	ds_read_b128 v[138:141], v128 offset:2048
	ds_read_b128 v[142:145], v128 offset:3072
	v_add_u32_e32 v128, vcc_hi, v173
	ds_read_b128 v[158:161], v128
	ds_read_b128 v[162:165], v128 offset:1024
	ds_read_b128 v[166:169], v128 offset:2048
	ds_read_b128 v[198:201], v128 offset:3072
	s_add_u32 s30, s50, s96
	s_addc_u32 s31, s51, 0
	s_mov_b32 m0, s87
	v_lshl_add_u64 v[252:253], s[30:31], 0, v[146:147]
	ds_read_b128 v[202:205], v190 offset:32768
	ds_read_b128 v[206:209], v190 offset:33792
	ds_read_b128 v[210:213], v190 offset:34816
	ds_read_b128 v[214:217], v190 offset:35840
	ds_read_b128 v[218:221], v190 offset:36864
	ds_read_b128 v[222:225], v190 offset:37888
	ds_read_b128 v[226:229], v190 offset:38912
	ds_read_b128 v[238:241], v190 offset:39936
	global_load_lds_dwordx4 v[252:253], off
	v_lshl_add_u64 v[252:253], s[30:31], 0, v[150:151]
	s_mov_b32 m0, s88
	s_nop 0
	global_load_lds_dwordx4 v[252:253], off
	s_waitcnt vmcnt(8)
	s_waitcnt lgkmcnt(0)
	s_setprio 1
	s_barrier
	v_mfma_f32_16x16x32_bf16 v[124:127], v[130:133], v[202:205], v[124:127]
	v_mfma_f32_16x16x32_bf16 v[120:123], v[138:141], v[202:205], v[120:123]
	v_mfma_f32_16x16x32_bf16 v[108:111], v[130:133], v[210:213], v[108:111]
	v_mfma_f32_16x16x32_bf16 v[104:107], v[138:141], v[210:213], v[104:107]
	v_mfma_f32_16x16x32_bf16 v[92:95], v[130:133], v[218:221], v[92:95]
	v_mfma_f32_16x16x32_bf16 v[88:91], v[138:141], v[218:221], v[88:91]
	v_mfma_f32_16x16x32_bf16 v[76:79], v[130:133], v[226:229], v[76:79]
	v_mfma_f32_16x16x32_bf16 v[72:75], v[138:141], v[226:229], v[72:75]
	v_mfma_f32_16x16x32_bf16 v[124:127], v[134:137], v[206:209], v[124:127]
	v_mfma_f32_16x16x32_bf16 v[120:123], v[142:145], v[206:209], v[120:123]
	v_mfma_f32_16x16x32_bf16 v[108:111], v[134:137], v[214:217], v[108:111]
	v_mfma_f32_16x16x32_bf16 v[104:107], v[142:145], v[214:217], v[104:107]
	v_mfma_f32_16x16x32_bf16 v[92:95], v[134:137], v[222:225], v[92:95]
	v_mfma_f32_16x16x32_bf16 v[88:91], v[142:145], v[222:225], v[88:91]
	v_mfma_f32_16x16x32_bf16 v[76:79], v[134:137], v[238:241], v[76:79]
	v_mfma_f32_16x16x32_bf16 v[72:75], v[142:145], v[238:241], v[72:75]
	v_mfma_f32_16x16x32_bf16 v[116:119], v[158:161], v[202:205], v[116:119]
	v_mfma_f32_16x16x32_bf16 v[112:115], v[166:169], v[202:205], v[112:115]
	v_mfma_f32_16x16x32_bf16 v[100:103], v[158:161], v[210:213], v[100:103]
	v_mfma_f32_16x16x32_bf16 v[96:99], v[166:169], v[210:213], v[96:99]
	v_mfma_f32_16x16x32_bf16 v[84:87], v[158:161], v[218:221], v[84:87]
	v_mfma_f32_16x16x32_bf16 v[80:83], v[166:169], v[218:221], v[80:83]
	v_mfma_f32_16x16x32_bf16 v[68:71], v[158:161], v[226:229], v[68:71]
	v_mfma_f32_16x16x32_bf16 v[64:67], v[166:169], v[226:229], v[64:67]
	v_mfma_f32_16x16x32_bf16 v[116:119], v[162:165], v[206:209], v[116:119]
	v_mfma_f32_16x16x32_bf16 v[112:115], v[198:201], v[206:209], v[112:115]
	v_mfma_f32_16x16x32_bf16 v[100:103], v[162:165], v[214:217], v[100:103]
	v_mfma_f32_16x16x32_bf16 v[96:99], v[198:201], v[214:217], v[96:99]
	v_mfma_f32_16x16x32_bf16 v[84:87], v[162:165], v[222:225], v[84:87]
	v_mfma_f32_16x16x32_bf16 v[80:83], v[198:201], v[222:225], v[80:83]
	v_mfma_f32_16x16x32_bf16 v[68:71], v[162:165], v[238:241], v[68:71]
	v_mfma_f32_16x16x32_bf16 v[64:67], v[198:201], v[238:241], v[64:67]
	s_barrier
	s_setprio 0
	s_add_i32 s30, s61, s82
	v_lshl_add_u64 v[170:171], v[170:171], 0, s[90:91]
	s_mov_b32 m0, s30
	ds_read_b128 v[202:205], v190 offset:49152
	ds_read_b128 v[206:209], v190 offset:50176
	ds_read_b128 v[210:213], v190 offset:51200
	ds_read_b128 v[214:217], v190 offset:52224
	ds_read_b128 v[218:221], v190 offset:53248
	ds_read_b128 v[222:225], v190 offset:54272
	ds_read_b128 v[226:229], v190 offset:55296
	ds_read_b128 v[238:241], v190 offset:56320
	global_load_lds_dwordx4 v[170:171], off
	v_lshl_add_u64 v[170:171], v[242:243], 0, s[90:91]
	s_add_i32 m0, s30, 0x2000
	s_add_i32 s30, vcc_hi, s82
	global_load_lds_dwordx4 v[170:171], off
	v_lshl_add_u64 v[170:171], v[244:245], 0, s[90:91]
	s_mov_b32 m0, s30
	s_nop 0
	global_load_lds_dwordx4 v[170:171], off
	v_lshl_add_u64 v[170:171], v[246:247], 0, s[90:91]
	s_add_i32 m0, s30, 0x2000
	s_nop 0
	global_load_lds_dwordx4 v[170:171], off
	v_lshl_add_u64 v[170:171], v[248:249], 0, s[90:91]
	s_mov_b32 m0, s53
	s_nop 0
	global_load_lds_dwordx4 v[170:171], off
	v_lshl_add_u64 v[170:171], v[250:251], 0, s[90:91]
	s_mov_b32 m0, s92
	s_nop 0
	global_load_lds_dwordx4 v[170:171], off
	s_waitcnt vmcnt(8)
	s_waitcnt lgkmcnt(0)
	s_setprio 1
	s_barrier
	v_mfma_f32_16x16x32_bf16 v[60:63], v[130:133], v[202:205], v[60:63]
	v_mfma_f32_16x16x32_bf16 v[56:59], v[138:141], v[202:205], v[56:59]
	v_mfma_f32_16x16x32_bf16 v[44:47], v[130:133], v[210:213], v[44:47]
	v_mfma_f32_16x16x32_bf16 v[40:43], v[138:141], v[210:213], v[40:43]
	v_mfma_f32_16x16x32_bf16 v[28:31], v[130:133], v[218:221], v[28:31]
	v_mfma_f32_16x16x32_bf16 v[24:27], v[138:141], v[218:221], v[24:27]
	v_mfma_f32_16x16x32_bf16 v[12:15], v[130:133], v[226:229], v[12:15]
	v_mfma_f32_16x16x32_bf16 v[8:11], v[138:141], v[226:229], v[8:11]
	v_mfma_f32_16x16x32_bf16 v[60:63], v[134:137], v[206:209], v[60:63]
	v_mfma_f32_16x16x32_bf16 v[56:59], v[142:145], v[206:209], v[56:59]
	v_mfma_f32_16x16x32_bf16 v[44:47], v[134:137], v[214:217], v[44:47]
	v_mfma_f32_16x16x32_bf16 v[40:43], v[142:145], v[214:217], v[40:43]
	v_mfma_f32_16x16x32_bf16 v[28:31], v[134:137], v[222:225], v[28:31]
	v_mfma_f32_16x16x32_bf16 v[24:27], v[142:145], v[222:225], v[24:27]
	v_mfma_f32_16x16x32_bf16 v[12:15], v[134:137], v[238:241], v[12:15]
	v_mfma_f32_16x16x32_bf16 v[8:11], v[142:145], v[238:241], v[8:11]
	v_mfma_f32_16x16x32_bf16 v[52:55], v[158:161], v[202:205], v[52:55]
	v_mfma_f32_16x16x32_bf16 v[48:51], v[166:169], v[202:205], v[48:51]
	v_mfma_f32_16x16x32_bf16 v[36:39], v[158:161], v[210:213], v[36:39]
	v_mfma_f32_16x16x32_bf16 v[32:35], v[166:169], v[210:213], v[32:35]
	v_mfma_f32_16x16x32_bf16 v[20:23], v[158:161], v[218:221], v[20:23]
	v_mfma_f32_16x16x32_bf16 v[16:19], v[166:169], v[218:221], v[16:19]
	v_mfma_f32_16x16x32_bf16 v[4:7], v[158:161], v[226:229], v[4:7]
	v_mfma_f32_16x16x32_bf16 v[0:3], v[166:169], v[226:229], v[0:3]
	v_mfma_f32_16x16x32_bf16 v[52:55], v[162:165], v[206:209], v[52:55]
	v_mfma_f32_16x16x32_bf16 v[48:51], v[198:201], v[206:209], v[48:51]
	v_mfma_f32_16x16x32_bf16 v[36:39], v[162:165], v[214:217], v[36:39]
	v_mfma_f32_16x16x32_bf16 v[32:35], v[198:201], v[214:217], v[32:35]
	v_mfma_f32_16x16x32_bf16 v[20:23], v[162:165], v[222:225], v[20:23]
	v_mfma_f32_16x16x32_bf16 v[16:19], v[198:201], v[222:225], v[16:19]
	v_mfma_f32_16x16x32_bf16 v[4:7], v[162:165], v[238:241], v[4:7]
	v_mfma_f32_16x16x32_bf16 v[0:3], v[198:201], v[238:241], v[0:3]
	s_barrier
	s_setprio 0
	s_add_u32 s45, s45, 0x100
	s_addc_u32 vcc_lo, vcc_lo, 0
	s_add_u32 s8, s8, 0x100
	s_addc_u32 s9, s9, 0
	s_cmp_ge_i32 s60, s5
	s_mov_b32 s50, s60
	s_cbranch_scc0 .LBB0_451

.LBB0_638:
	s_add_u32 s26, s24, 0xfffc0080
	s_addc_u32 s27, s25, -1
	s_add_i32 s30, 0, 0x10000
	s_cmp_eq_u32 s51, 12
	s_cselect_b32 s29, s15, s27
	s_cselect_b32 s28, s21, s26
	s_cselect_b32 s27, s13, s50
	s_cselect_b32 s26, s23, s49
	s_add_i32 s31, 0, 0x14000
	v_add_u32_e32 v156, s30, v145
	v_add_u32_e32 v172, s31, v145
	ds_read_b128 v[140:143], v156
	ds_read_b128 v[148:151], v156 offset:1024
	ds_read_b128 v[152:155], v156 offset:2048
	ds_read_b128 v[156:159], v156 offset:3072
	ds_read_b128 v[160:163], v172
	ds_read_b128 v[164:167], v172 offset:1024
	ds_read_b128 v[168:171], v172 offset:2048
	ds_read_b128 v[172:175], v172 offset:3072
	v_lshl_add_u64 v[176:177], s[24:25], 0, v[138:139]
	s_add_i32 m0, s1, 0xc000
	ds_read_b128 v[198:201], v147
	ds_read_b128 v[202:205], v147 offset:1024
	ds_read_b128 v[206:209], v147 offset:2048
	ds_read_b128 v[210:213], v147 offset:3072
	ds_read_b128 v[214:217], v147 offset:4096
	ds_read_b128 v[218:221], v147 offset:5120
	ds_read_b128 v[222:225], v147 offset:6144
	ds_read_b128 v[226:229], v147 offset:7168
	global_load_lds_dwordx4 v[176:177], off
	v_lshl_add_u64 v[176:177], s[24:25], 0, v[136:137]
	s_add_i32 m0, s1, 0xe000
	s_nop 0
	global_load_lds_dwordx4 v[176:177], off
	s_waitcnt vmcnt(8)
	s_waitcnt lgkmcnt(0)
	s_setprio 1
	s_barrier
	v_mfma_f32_16x16x32_bf16 v[120:123], v[140:143], v[198:201], v[120:123]
	v_mfma_f32_16x16x32_bf16 v[112:115], v[152:155], v[198:201], v[112:115]
	v_mfma_f32_16x16x32_bf16 v[104:107], v[140:143], v[206:209], v[104:107]
	v_mfma_f32_16x16x32_bf16 v[96:99], v[152:155], v[206:209], v[96:99]
	v_mfma_f32_16x16x32_bf16 v[88:91], v[140:143], v[214:217], v[88:91]
	v_mfma_f32_16x16x32_bf16 v[80:83], v[152:155], v[214:217], v[80:83]
	v_mfma_f32_16x16x32_bf16 v[72:75], v[140:143], v[222:225], v[72:75]
	v_mfma_f32_16x16x32_bf16 v[64:67], v[152:155], v[222:225], v[64:67]
	v_mfma_f32_16x16x32_bf16 v[120:123], v[148:151], v[202:205], v[120:123]
	v_mfma_f32_16x16x32_bf16 v[112:115], v[156:159], v[202:205], v[112:115]
	v_mfma_f32_16x16x32_bf16 v[104:107], v[148:151], v[210:213], v[104:107]
	v_mfma_f32_16x16x32_bf16 v[96:99], v[156:159], v[210:213], v[96:99]
	v_mfma_f32_16x16x32_bf16 v[88:91], v[148:151], v[218:221], v[88:91]
	v_mfma_f32_16x16x32_bf16 v[80:83], v[156:159], v[218:221], v[80:83]
	v_mfma_f32_16x16x32_bf16 v[72:75], v[148:151], v[226:229], v[72:75]
	v_mfma_f32_16x16x32_bf16 v[64:67], v[156:159], v[226:229], v[64:67]
	v_mfma_f32_16x16x32_bf16 v[124:127], v[160:163], v[198:201], v[124:127]
	v_mfma_f32_16x16x32_bf16 v[116:119], v[168:171], v[198:201], v[116:119]
	v_mfma_f32_16x16x32_bf16 v[108:111], v[160:163], v[206:209], v[108:111]
	v_mfma_f32_16x16x32_bf16 v[100:103], v[168:171], v[206:209], v[100:103]
	v_mfma_f32_16x16x32_bf16 v[92:95], v[160:163], v[214:217], v[92:95]
	v_mfma_f32_16x16x32_bf16 v[84:87], v[168:171], v[214:217], v[84:87]
	v_mfma_f32_16x16x32_bf16 v[76:79], v[160:163], v[222:225], v[76:79]
	v_mfma_f32_16x16x32_bf16 v[68:71], v[168:171], v[222:225], v[68:71]
	v_mfma_f32_16x16x32_bf16 v[124:127], v[164:167], v[202:205], v[124:127]
	v_mfma_f32_16x16x32_bf16 v[116:119], v[172:175], v[202:205], v[116:119]
	v_mfma_f32_16x16x32_bf16 v[108:111], v[164:167], v[210:213], v[108:111]
	v_mfma_f32_16x16x32_bf16 v[100:103], v[172:175], v[210:213], v[100:103]
	v_mfma_f32_16x16x32_bf16 v[92:95], v[164:167], v[218:221], v[92:95]
	v_mfma_f32_16x16x32_bf16 v[84:87], v[172:175], v[218:221], v[84:87]
	v_mfma_f32_16x16x32_bf16 v[76:79], v[164:167], v[226:229], v[76:79]
	v_mfma_f32_16x16x32_bf16 v[68:71], v[172:175], v[226:229], v[68:71]
	s_barrier
	s_setprio 0
	s_add_i32 s30, s30, s45
	v_lshl_add_u64 v[176:177], s[26:27], 0, v[128:129]
	s_mov_b32 m0, s30
	ds_read_b128 v[198:201], v147 offset:16384
	ds_read_b128 v[202:205], v147 offset:17408
	ds_read_b128 v[206:209], v147 offset:18432
	ds_read_b128 v[210:213], v147 offset:19456
	ds_read_b128 v[214:217], v147 offset:20480
	ds_read_b128 v[218:221], v147 offset:21504
	ds_read_b128 v[222:225], v147 offset:22528
	ds_read_b128 v[226:229], v147 offset:23552
	global_load_lds_dwordx4 v[176:177], off
	s_add_i32 m0, s30, 0x2000
	s_add_u32 s52, s26, 0x40000
	v_lshl_add_u64 v[238:239], s[26:27], 0, v[130:131]
	s_addc_u32 s53, s27, 0
	s_add_i32 s30, s31, s45
	global_load_lds_dwordx4 v[238:239], off
	v_lshl_add_u64 v[240:241], s[52:53], 0, v[128:129]
	s_mov_b32 m0, s30
	v_lshl_add_u64 v[242:243], s[28:29], 0, v[132:133]
	global_load_lds_dwordx4 v[240:241], off
	v_lshl_add_u64 v[240:241], s[52:53], 0, v[130:131]
	s_add_i32 m0, s30, 0x2000
	s_nop 0
	global_load_lds_dwordx4 v[240:241], off
	v_lshl_add_u64 v[240:241], s[28:29], 0, v[134:135]
	s_mov_b32 m0, s1
	s_nop 0
	global_load_lds_dwordx4 v[240:241], off
	s_mov_b32 m0, s43
	s_nop 0
	global_load_lds_dwordx4 v[242:243], off
	s_waitcnt vmcnt(8)
	s_waitcnt lgkmcnt(0)
	s_setprio 1
	s_barrier
	v_mfma_f32_16x16x32_bf16 v[56:59], v[140:143], v[198:201], v[56:59]
	v_mfma_f32_16x16x32_bf16 v[48:51], v[152:155], v[198:201], v[48:51]
	v_mfma_f32_16x16x32_bf16 v[40:43], v[140:143], v[206:209], v[40:43]
	v_mfma_f32_16x16x32_bf16 v[32:35], v[152:155], v[206:209], v[32:35]
	v_mfma_f32_16x16x32_bf16 v[24:27], v[140:143], v[214:217], v[24:27]
	v_mfma_f32_16x16x32_bf16 v[16:19], v[152:155], v[214:217], v[16:19]
	v_mfma_f32_16x16x32_bf16 v[8:11], v[140:143], v[222:225], v[8:11]
	v_mfma_f32_16x16x32_bf16 v[0:3], v[152:155], v[222:225], v[0:3]
	v_mfma_f32_16x16x32_bf16 v[56:59], v[148:151], v[202:205], v[56:59]
	v_mfma_f32_16x16x32_bf16 v[48:51], v[156:159], v[202:205], v[48:51]
	v_mfma_f32_16x16x32_bf16 v[40:43], v[148:151], v[210:213], v[40:43]
	v_mfma_f32_16x16x32_bf16 v[32:35], v[156:159], v[210:213], v[32:35]
	v_mfma_f32_16x16x32_bf16 v[24:27], v[148:151], v[218:221], v[24:27]
	v_mfma_f32_16x16x32_bf16 v[16:19], v[156:159], v[218:221], v[16:19]
	v_mfma_f32_16x16x32_bf16 v[8:11], v[148:151], v[226:229], v[8:11]
	v_mfma_f32_16x16x32_bf16 v[0:3], v[156:159], v[226:229], v[0:3]
	v_mfma_f32_16x16x32_bf16 v[60:63], v[160:163], v[198:201], v[60:63]
	v_mfma_f32_16x16x32_bf16 v[52:55], v[168:171], v[198:201], v[52:55]
	v_mfma_f32_16x16x32_bf16 v[44:47], v[160:163], v[206:209], v[44:47]
	v_mfma_f32_16x16x32_bf16 v[36:39], v[168:171], v[206:209], v[36:39]
	v_mfma_f32_16x16x32_bf16 v[28:31], v[160:163], v[214:217], v[28:31]
	v_mfma_f32_16x16x32_bf16 v[20:23], v[168:171], v[214:217], v[20:23]
	v_mfma_f32_16x16x32_bf16 v[12:15], v[160:163], v[222:225], v[12:15]
	v_mfma_f32_16x16x32_bf16 v[4:7], v[168:171], v[222:225], v[4:7]
	v_mfma_f32_16x16x32_bf16 v[60:63], v[164:167], v[202:205], v[60:63]
	v_mfma_f32_16x16x32_bf16 v[52:55], v[172:175], v[202:205], v[52:55]
	v_mfma_f32_16x16x32_bf16 v[44:47], v[164:167], v[210:213], v[44:47]
	v_mfma_f32_16x16x32_bf16 v[36:39], v[172:175], v[210:213], v[36:39]
	v_mfma_f32_16x16x32_bf16 v[28:31], v[164:167], v[218:221], v[28:31]
	v_mfma_f32_16x16x32_bf16 v[20:23], v[172:175], v[218:221], v[20:23]
	v_mfma_f32_16x16x32_bf16 v[12:15], v[164:167], v[226:229], v[12:15]
	v_mfma_f32_16x16x32_bf16 v[4:7], v[172:175], v[226:229], v[4:7]
	s_barrier
	s_setprio 0
	s_add_i32 s30, 0, 0x18000
	s_add_i32 s31, 0, 0x1c000
	v_add_u32_e32 v156, s30, v145
	v_add_u32_e32 v172, s31, v145
	ds_read_b128 v[140:143], v156
	ds_read_b128 v[148:151], v156 offset:1024
	ds_read_b128 v[152:155], v156 offset:2048
	ds_read_b128 v[156:159], v156 offset:3072
	ds_read_b128 v[160:163], v172
	ds_read_b128 v[164:167], v172 offset:1024
	ds_read_b128 v[168:171], v172 offset:2048
	ds_read_b128 v[172:175], v172 offset:3072
	s_add_u32 s28, s28, 0x40000
	s_addc_u32 s29, s29, 0
	s_mov_b32 m0, s46
	v_lshl_add_u64 v[244:245], s[28:29], 0, v[134:135]
	ds_read_b128 v[198:201], v147 offset:32768
	ds_read_b128 v[202:205], v147 offset:33792
	ds_read_b128 v[206:209], v147 offset:34816
	ds_read_b128 v[210:213], v147 offset:35840
	ds_read_b128 v[214:217], v147 offset:36864
	ds_read_b128 v[218:221], v147 offset:37888
	ds_read_b128 v[222:225], v147 offset:38912
	ds_read_b128 v[226:229], v147 offset:39936
	global_load_lds_dwordx4 v[244:245], off
	v_lshl_add_u64 v[244:245], s[28:29], 0, v[132:133]
	s_mov_b32 m0, s47
	s_nop 0
	global_load_lds_dwordx4 v[244:245], off
	s_waitcnt vmcnt(8)
	s_waitcnt lgkmcnt(0)
	s_setprio 1
	s_barrier
	v_mfma_f32_16x16x32_bf16 v[120:123], v[140:143], v[198:201], v[120:123]
	v_mfma_f32_16x16x32_bf16 v[112:115], v[152:155], v[198:201], v[112:115]
	v_mfma_f32_16x16x32_bf16 v[104:107], v[140:143], v[206:209], v[104:107]
	v_mfma_f32_16x16x32_bf16 v[96:99], v[152:155], v[206:209], v[96:99]
	v_mfma_f32_16x16x32_bf16 v[88:91], v[140:143], v[214:217], v[88:91]
	v_mfma_f32_16x16x32_bf16 v[80:83], v[152:155], v[214:217], v[80:83]
	v_mfma_f32_16x16x32_bf16 v[72:75], v[140:143], v[222:225], v[72:75]
	v_mfma_f32_16x16x32_bf16 v[64:67], v[152:155], v[222:225], v[64:67]
	v_mfma_f32_16x16x32_bf16 v[120:123], v[148:151], v[202:205], v[120:123]
	v_mfma_f32_16x16x32_bf16 v[112:115], v[156:159], v[202:205], v[112:115]
	v_mfma_f32_16x16x32_bf16 v[104:107], v[148:151], v[210:213], v[104:107]
	v_mfma_f32_16x16x32_bf16 v[96:99], v[156:159], v[210:213], v[96:99]
	v_mfma_f32_16x16x32_bf16 v[88:91], v[148:151], v[218:221], v[88:91]
	v_mfma_f32_16x16x32_bf16 v[80:83], v[156:159], v[218:221], v[80:83]
	v_mfma_f32_16x16x32_bf16 v[72:75], v[148:151], v[226:229], v[72:75]
	v_mfma_f32_16x16x32_bf16 v[64:67], v[156:159], v[226:229], v[64:67]
	v_mfma_f32_16x16x32_bf16 v[124:127], v[160:163], v[198:201], v[124:127]
	v_mfma_f32_16x16x32_bf16 v[116:119], v[168:171], v[198:201], v[116:119]
	v_mfma_f32_16x16x32_bf16 v[108:111], v[160:163], v[206:209], v[108:111]
	v_mfma_f32_16x16x32_bf16 v[100:103], v[168:171], v[206:209], v[100:103]
	v_mfma_f32_16x16x32_bf16 v[92:95], v[160:163], v[214:217], v[92:95]
	v_mfma_f32_16x16x32_bf16 v[84:87], v[168:171], v[214:217], v[84:87]
	v_mfma_f32_16x16x32_bf16 v[76:79], v[160:163], v[222:225], v[76:79]
	v_mfma_f32_16x16x32_bf16 v[68:71], v[168:171], v[222:225], v[68:71]
	v_mfma_f32_16x16x32_bf16 v[124:127], v[164:167], v[202:205], v[124:127]
	v_mfma_f32_16x16x32_bf16 v[116:119], v[172:175], v[202:205], v[116:119]
	v_mfma_f32_16x16x32_bf16 v[108:111], v[164:167], v[210:213], v[108:111]
	v_mfma_f32_16x16x32_bf16 v[100:103], v[172:175], v[210:213], v[100:103]
	v_mfma_f32_16x16x32_bf16 v[92:95], v[164:167], v[218:221], v[92:95]
	v_mfma_f32_16x16x32_bf16 v[84:87], v[172:175], v[218:221], v[84:87]
	v_mfma_f32_16x16x32_bf16 v[76:79], v[164:167], v[226:229], v[76:79]
	v_mfma_f32_16x16x32_bf16 v[68:71], v[172:175], v[226:229], v[68:71]
	s_barrier
	s_setprio 0
	s_add_i32 s28, s30, s45
	v_lshl_add_u64 v[176:177], v[176:177], 0, s[90:91]
	s_mov_b32 m0, s28
	ds_read_b128 v[198:201], v147 offset:49152
	ds_read_b128 v[202:205], v147 offset:50176
	ds_read_b128 v[206:209], v147 offset:51200
	ds_read_b128 v[210:213], v147 offset:52224
	ds_read_b128 v[214:217], v147 offset:53248
	ds_read_b128 v[218:221], v147 offset:54272
	ds_read_b128 v[222:225], v147 offset:55296
	ds_read_b128 v[226:229], v147 offset:56320
	global_load_lds_dwordx4 v[176:177], off
	s_add_i32 m0, s28, 0x2000
	s_add_u32 s26, s26, 0x40080
	v_lshl_add_u64 v[176:177], v[238:239], 0, s[90:91]
	s_addc_u32 s27, s27, 0
	s_add_i32 s28, s31, s45
	global_load_lds_dwordx4 v[176:177], off
	v_lshl_add_u64 v[176:177], s[26:27], 0, v[128:129]
	s_mov_b32 m0, s28
	s_nop 0
	global_load_lds_dwordx4 v[176:177], off
	v_lshl_add_u64 v[176:177], s[26:27], 0, v[130:131]
	s_add_i32 m0, s28, 0x2000
	s_nop 0
	global_load_lds_dwordx4 v[176:177], off
	v_lshl_add_u64 v[176:177], v[240:241], 0, s[90:91]
	s_mov_b32 m0, s0
	s_nop 0
	global_load_lds_dwordx4 v[176:177], off
	v_lshl_add_u64 v[176:177], v[242:243], 0, s[90:91]
	s_mov_b32 m0, s4
	s_nop 0
	global_load_lds_dwordx4 v[176:177], off
	s_waitcnt vmcnt(8)
	s_waitcnt lgkmcnt(0)
	s_setprio 1
	s_barrier
	v_mfma_f32_16x16x32_bf16 v[56:59], v[140:143], v[198:201], v[56:59]
	v_mfma_f32_16x16x32_bf16 v[48:51], v[152:155], v[198:201], v[48:51]
	v_mfma_f32_16x16x32_bf16 v[40:43], v[140:143], v[206:209], v[40:43]
	v_mfma_f32_16x16x32_bf16 v[32:35], v[152:155], v[206:209], v[32:35]
	v_mfma_f32_16x16x32_bf16 v[24:27], v[140:143], v[214:217], v[24:27]
	v_mfma_f32_16x16x32_bf16 v[16:19], v[152:155], v[214:217], v[16:19]
	v_mfma_f32_16x16x32_bf16 v[8:11], v[140:143], v[222:225], v[8:11]
	v_mfma_f32_16x16x32_bf16 v[0:3], v[152:155], v[222:225], v[0:3]
	v_mfma_f32_16x16x32_bf16 v[56:59], v[148:151], v[202:205], v[56:59]
	v_mfma_f32_16x16x32_bf16 v[48:51], v[156:159], v[202:205], v[48:51]
	v_mfma_f32_16x16x32_bf16 v[40:43], v[148:151], v[210:213], v[40:43]
	v_mfma_f32_16x16x32_bf16 v[32:35], v[156:159], v[210:213], v[32:35]
	v_mfma_f32_16x16x32_bf16 v[24:27], v[148:151], v[218:221], v[24:27]
	v_mfma_f32_16x16x32_bf16 v[16:19], v[156:159], v[218:221], v[16:19]
	v_mfma_f32_16x16x32_bf16 v[8:11], v[148:151], v[226:229], v[8:11]
	v_mfma_f32_16x16x32_bf16 v[0:3], v[156:159], v[226:229], v[0:3]
	v_mfma_f32_16x16x32_bf16 v[60:63], v[160:163], v[198:201], v[60:63]
	v_mfma_f32_16x16x32_bf16 v[52:55], v[168:171], v[198:201], v[52:55]
	v_mfma_f32_16x16x32_bf16 v[44:47], v[160:163], v[206:209], v[44:47]
	v_mfma_f32_16x16x32_bf16 v[36:39], v[168:171], v[206:209], v[36:39]
	v_mfma_f32_16x16x32_bf16 v[28:31], v[160:163], v[214:217], v[28:31]
	v_mfma_f32_16x16x32_bf16 v[20:23], v[168:171], v[214:217], v[20:23]
	v_mfma_f32_16x16x32_bf16 v[12:15], v[160:163], v[222:225], v[12:15]
	v_mfma_f32_16x16x32_bf16 v[4:7], v[168:171], v[222:225], v[4:7]
	v_mfma_f32_16x16x32_bf16 v[60:63], v[164:167], v[202:205], v[60:63]
	v_mfma_f32_16x16x32_bf16 v[52:55], v[172:175], v[202:205], v[52:55]
	v_mfma_f32_16x16x32_bf16 v[44:47], v[164:167], v[210:213], v[44:47]
	v_mfma_f32_16x16x32_bf16 v[36:39], v[172:175], v[210:213], v[36:39]
	v_mfma_f32_16x16x32_bf16 v[28:31], v[164:167], v[218:221], v[28:31]
	v_mfma_f32_16x16x32_bf16 v[20:23], v[172:175], v[218:221], v[20:23]
	v_mfma_f32_16x16x32_bf16 v[12:15], v[164:167], v[226:229], v[12:15]
	v_mfma_f32_16x16x32_bf16 v[4:7], v[172:175], v[226:229], v[4:7]
	s_barrier
	s_setprio 0
	s_add_i32 s51, s51, 2
	s_add_u32 s49, s49, 0x100
	s_addc_u32 s50, s50, 0
	s_add_u32 s24, s24, 0x100
	s_addc_u32 s25, s25, 0
	s_cmp_gt_u32 s51, 13
	s_cbranch_scc0 .LBB0_638
	s_and_b64 vcc, exec, s[10:11]
	s_cbranch_vccz .LBB0_641
	s_barrier
